# attn: K-frag prefetch + fast-path rewrite (no phi copies, V prefetch), btab built once per g, early tile0 loads, head-major conflict-free bias table
# speedup vs baseline: 1.0385x; 1.0385x over previous
.LBB0_1259:
	s_mov_b32 s98, -1
	s_cmp_lt_i32 s46, 11
	s_cselect_b64 s[2:3], -1, 0
	s_and_b64 s[8:9], s[2:3], s[0:1]
	s_andn2_b64 vcc, exec, s[8:9]
	s_cbranch_vccnz .LBB0_1478
	v_mov_b32_e32 v107, v188
	s_movk_i32 s0, 0x80
	s_nop 0
	v_readfirstlane_b32 s6, v107
	v_cmp_gt_i32_e32 vcc, s0, v107
	s_and_saveexec_b64 s[2:3], vcc
	s_cbranch_execz .LBB0_1264
	v_cmp_lt_i32_e32 vcc, 15, v107
	v_mov_b32_e32 v0, v107
	s_and_saveexec_b64 s[4:5], vcc
	s_cbranch_execz .LBB0_1263
	v_cvt_f32_u32_e32 v0, v107
	s_mov_b32 s0, 0x800000
	s_mov_b32 s1, 0x7f800000
	s_mov_b32 s7, 0x40051592
	v_mul_f32_e32 v0, 0x3d800000, v0
	v_cmp_gt_f32_e32 vcc, s0, v0
	s_mov_b32 s0, 0x3f317217
	s_waitcnt lgkmcnt(0)
	v_cndmask_b32_e64 v1, 0, 32, vcc
	v_ldexp_f32 v0, v0, v1
	v_log_f32_e32 v0, v0
	v_mov_b32_e32 v1, 0x41b17218
	v_cndmask_b32_e32 v1, 0, v1, vcc
	v_mul_f32_e32 v2, 0x3f317217, v0
	v_fma_f32 v2, v0, s0, -v2
	v_fmamk_f32 v2, v0, 0x3377d1cf, v2
	v_fmac_f32_e32 v2, 0x3f317217, v0
	v_cmp_lt_f32_e64 s[0:1], |v0|, s1
	s_nop 1
	v_cndmask_b32_e64 v0, v0, v2, s[0:1]
	v_sub_f32_e32 v0, v0, v1
	v_div_scale_f32 v1, s[0:1], s7, s7, v0
	v_rcp_f32_e32 v2, v1
	s_nop 0
	v_fma_f32 v3, -v1, v2, 1.0
	v_fmac_f32_e32 v2, v3, v2
	v_div_scale_f32 v3, vcc, v0, s7, v0
	v_mul_f32_e32 v4, v3, v2
	v_fma_f32 v5, -v1, v4, v3
	v_fmac_f32_e32 v4, v5, v2
	v_fma_f32 v1, -v1, v4, v3
	v_div_fmas_f32 v1, v1, v2, v4
	v_div_fixup_f32 v0, v1, s7, v0
	v_mul_f32_e32 v0, 0x41800000, v0
	v_cvt_i32_f32_e32 v0, v0
	v_min_i32_e32 v0, 15, v0
	v_add_u32_e32 v0, 16, v0

.LBB0_1266:
	s_cmp_lt_i32 s72, 1
	s_cbranch_scc1 .LBB0_1477
	s_ashr_i32 s4, s33, 6
	s_bfe_u32 s3, s33, 0x30003
	s_add_u32 s56, s44, 0x17800000
	s_addc_u32 s57, s45, 0
	s_add_u32 s76, s44, 0x34800000
	s_addc_u32 s77, s45, 0
	s_add_u32 s73, s44, 0x35c40000
	v_writelane_b32 v235, s8, 49
	s_addc_u32 s19, s45, 0
	s_lshl_b32 s1, s33, 4
	v_writelane_b32 v235, s9, 50
	s_and_b32 s1, s1, 0x70
	v_writelane_b32 v235, s4, 51
	s_add_i32 s1, s1, s4
	v_writelane_b32 v235, s1, 52
	s_xor_b32 s1, s3, 15
	v_writelane_b32 v235, s1, 53
	s_or_b32 s1, s3, 16
	v_writelane_b32 v235, s1, 54
	s_ashr_i32 s0, s6, 6
	v_writelane_b32 v235, s3, 55
	s_xor_b32 s1, s3, 31
	v_and_b32_e32 v1, 63, v107
	v_writelane_b32 v235, s1, 56
	s_lshl_b32 s1, s0, 5
	s_lshl_b32 s0, s0, 13
	s_add_i32 s0, s0, 0
	v_lshlrev_b32_e32 v8, 2, v1
	s_ashr_i32 s21, s6, 7
	v_bfe_u32 v3, v107, 5, 1
	s_add_i32 s6, s0, 0x12c00
	v_xor_b32_e32 v155, 0x80, v8
	v_or_b32_e32 v8, 32, v1
	s_mov_b32 s0, 0xffffffc
	s_and_b32 s60, s1, 32
	v_mul_u32_u24_e32 v158, 0x90, v8
	v_mul_lo_u32 v159, v3, s0
	v_lshlrev_b32_e32 v8, 1, v107
	s_lshl_b32 s0, s21, 6
	v_and_b32_e32 v152, 31, v107
	v_lshlrev_b32_e32 v153, 2, v3
	v_and_b32_e32 v11, 32, v8
	v_lshlrev_b32_e32 v8, 3, v107
	s_or_b32 s0, s60, s0
	v_add_u32_e32 v0, 0, v153
	s_movk_i32 s1, 0x540
	v_and_b32_e32 v13, 24, v8
	v_or_b32_e32 v8, s0, v152
	s_movk_i32 s7, 0x84
	v_cmp_gt_i32_e64 s[22:23], s1, v107
	v_mad_u64_u32 v[110:111], s[0:1], v8, s7, v[0:1]
	v_cmp_gt_i32_e64 s[0:1], 64, v107
	s_add_i32 s2, 0, 0x11400
	v_ashrrev_i32_e32 v108, 3, v107
	v_writelane_b32 v235, s0, 57
	s_movk_i32 s68, 0xc00
	v_lshlrev_b32_e32 v14, 2, v107
	v_writelane_b32 v235, s1, 58
	s_lshl_b32 s0, s60, 2
	s_add_i32 s0, s0, s2
	v_lshl_add_u32 v194, v152, 2, s0
	v_mad_i64_i32 v[112:113], s[0:1], v108, s68, 0
	v_mad_u32_u24 v156, v3, 12, v0
	v_add_u32_e32 v111, s2, v14
	v_mul_lo_u32 v0, v108, s7
	v_lshl_add_u32 v193, v108, 2, s2
	v_ashrrev_i32_e32 v109, 31, v108
	s_add_i32 s2, 0, 0x11500
	s_lshl_b32 s0, s21, 2
	v_and_b32_e32 v5, 7, v107
	s_movk_i32 s3, 0x90
	v_add_u32_e32 v192, 0, v0
	s_mul_i32 s69, s21, 0x540
	s_add_i32 s69, s69, s2
	v_mov_b32_e32 v0, s6
	v_lshlrev_b64 v[114:115], 8, v[108:109]
	s_mov_b64 s[0:1], 0x4000
	v_lshlrev_b32_e32 v9, 4, v1
	v_cmp_gt_u32_e64 s[4:5], 32, v1
	v_mad_u32_u24 v15, v152, s3, v0
	v_lshl_add_u64 v[0:1], v[114:115], 0, s[0:1]
	v_cmp_lt_u32_e64 s[0:1], 4, v5
	v_lshlrev_b32_e32 v191, 2, v5
	v_or_b32_e32 v198, 2, v191
	v_writelane_b32 v235, s0, 59
	v_or_b32_e32 v199, 3, v191
	v_lshlrev_b32_e32 v2, 3, v3
	v_writelane_b32 v235, s1, 60
	v_cmp_lt_u32_e64 s[0:1], 5, v5
	v_mul_lo_u32 v6, v108, s3
	v_lshlrev_b32_e32 v7, 4, v5
	v_writelane_b32 v235, s0, 61
	v_lshrrev_b32_e32 v3, 2, v107
	v_bfe_u32 v8, v107, 3, 3
	v_writelane_b32 v235, s1, 62
	v_cmp_eq_u32_e64 s[0:1], 7, v5
	v_and_or_b32 v3, v3, 3, v153
	v_add3_u32 v195, 0, v6, v7
	v_writelane_b32 v235, s0, 33
	v_add_u32_e32 v16, s6, v7
	v_add_u32_e32 v109, v192, v7
	v_writelane_b32 v235, s1, 34
	v_cmp_lt_u32_e64 s[0:1], 5, v198
	v_lshlrev_b32_e32 v6, 10, v8
	v_or_b32_e32 v7, 8, v8
	v_writelane_b32 v235, s0, 63
	s_mov_b32 s41, 0
	v_lshlrev_b32_e32 v4, 3, v5
	v_writelane_b32 v234, s1, 0
	v_cmp_lt_u32_e64 s[0:1], 9, v198
	v_cmp_eq_u32_e64 s[78:79], 0, v5
	v_mul_u32_u24_e32 v17, 0x90, v8
	v_writelane_b32 v234, s0, 1
	v_mul_u32_u24_e32 v18, 0x90, v7
	v_lshlrev_b32_e32 v8, 10, v7
	v_writelane_b32 v234, s1, 2
	v_cmp_lt_u32_e64 s[0:1], 13, v198
	v_or_b32_e32 v10, 0x4000, v6
	v_or_b32_e32 v12, 0x6000, v6
	v_writelane_b32 v234, s0, 3
	v_mad_u32_u24 v3, v3, s3, 0
	v_or_b32_e32 v154, s60, v152
	v_writelane_b32 v234, s1, 4
	v_cmp_lt_u32_e64 s[0:1], 17, v198
	v_mov_b32_e32 v32, 0
	v_mul_u32_u24_e32 v157, 0x90, v152
	v_writelane_b32 v234, s0, 5
	v_add_u32_e32 v160, 0xffffffe, v159
	v_add_u32_e32 v161, 0xffffffd, v159
	v_writelane_b32 v234, s1, 6
	v_cmp_lt_u32_e64 s[0:1], 21, v198
	v_add_u32_e32 v162, 0xffffff8, v159
	v_add_u32_e32 v163, 0xffffff7, v159
	v_writelane_b32 v234, s0, 7
	v_add_u32_e32 v164, 0xffffff6, v159
	v_add_u32_e32 v165, 0xffffff5, v159
	v_writelane_b32 v234, s1, 8
	v_cmp_lt_u32_e64 s[0:1], 25, v198
	v_add_u32_e32 v166, 0xffffff0, v159
	v_add_u32_e32 v167, 0xfffffef, v159
	v_writelane_b32 v234, s0, 9
	v_add_u32_e32 v168, 0xfffffee, v159
	v_add_u32_e32 v169, 0xfffffed, v159
	v_writelane_b32 v234, s1, 10
	v_cmp_lt_u32_e64 s[0:1], 4, v199
	v_add_u32_e32 v170, 0xfffffe8, v159
	v_add_u32_e32 v171, 0xfffffe7, v159
	v_writelane_b32 v234, s0, 11
	v_add_u32_e32 v172, 0xfffffe6, v159
	v_add_u32_e32 v173, 0xfffffe5, v159
	v_writelane_b32 v234, s1, 12
	v_cmp_lt_u32_e64 s[0:1], 5, v199
	v_add_u32_e32 v174, 0xfffffe0, v159
	v_add_u32_e32 v175, 0xfffffdf, v159
	v_writelane_b32 v234, s0, 13
	v_add_u32_e32 v176, 0xfffffde, v159
	v_add_u32_e32 v177, 0xfffffdd, v159
	v_writelane_b32 v234, s1, 14
	v_cmp_lt_u32_e64 s[0:1], 6, v199
	v_add_u32_e32 v178, 0xfffffd8, v159
	v_add_u32_e32 v179, 0xfffffd7, v159
	v_writelane_b32 v234, s0, 15
	v_add_u32_e32 v180, 0xfffffd6, v159
	v_add_u32_e32 v181, 0xfffffd5, v159
	v_writelane_b32 v234, s1, 16
	v_cmp_lt_u32_e64 s[0:1], 8, v199
	v_add_u32_e32 v182, 0xfffffd0, v159
	v_add_u32_e32 v183, 0xfffffcf, v159
	v_writelane_b32 v234, s0, 17
	v_add_u32_e32 v184, 0xfffffce, v159
	v_add_u32_e32 v185, 0xfffffcd, v159
	v_writelane_b32 v234, s1, 18
	v_cmp_lt_u32_e64 s[0:1], 9, v199
	v_add_u32_e32 v186, 0xfffffc8, v159
	v_add_u32_e32 v187, 0xfffffc7, v159
	v_writelane_b32 v234, s0, 19
	v_add_u32_e32 v189, 0xfffffc6, v159
	v_add_u32_e32 v190, 0xfffffc5, v159
	v_writelane_b32 v234, s1, 20
	v_cmp_lt_u32_e64 s[0:1], 10, v199
	s_mov_b32 s61, s41
	v_and_b32_e32 v196, 3, v107
	v_writelane_b32 v234, s0, 21
	v_or_b32_e32 v197, 1, v191
	v_cmp_ne_u32_e64 s[10:11], 0, v5
	v_writelane_b32 v234, s1, 22
	v_cmp_lt_u32_e64 s[0:1], 12, v199
	v_cmp_lt_u32_e64 s[12:13], 1, v5
	v_cmp_lt_u32_e64 s[14:15], 2, v5
	v_writelane_b32 v234, s0, 23
	v_cmp_lt_u32_e64 s[16:17], 3, v5
	v_lshlrev_b32_e64 v200, v191, 1
	v_writelane_b32 v234, s1, 24
	v_cmp_lt_u32_e64 s[0:1], 13, v199
	v_lshlrev_b32_e64 v201, v191, 2
	v_lshlrev_b32_e64 v202, v191, 4
	v_writelane_b32 v234, s0, 25
	v_lshlrev_b32_e64 v203, v191, 8
	v_add3_u32 v204, v3, v11, v13
	v_writelane_b32 v234, s1, 26
	v_cmp_lt_u32_e64 s[0:1], 14, v199
	v_and_b32_e32 v205, -4, v107
	v_mul_u32_u24_e32 v252, 0x540, v196
	v_add3_u32 v205, v205, v252, s2
	v_lshlrev_b32_e32 v116, 1, v2
	v_writelane_b32 v234, s0, 27
	s_movk_i32 s20, 0xc0
	s_add_i32 s71, 0, 0x12a00
	v_writelane_b32 v234, s1, 28
	v_cmp_lt_u32_e64 s[0:1], 16, v199
	v_lshlrev_b64 v[118:119], 1, v[0:1]
	s_mov_b32 s70, 0xff800000
	v_writelane_b32 v234, s0, 29
	v_lshlrev_b32_e32 v120, 1, v4
	s_movk_i32 s67, 0x1ff
	v_writelane_b32 v234, s1, 30
	v_cmp_lt_u32_e64 s[0:1], 17, v199
	v_add_u32_e32 v206, v15, v2
	v_add_u32_e32 v207, v16, v17
	v_writelane_b32 v234, s0, 31
	v_lshlrev_b32_e32 v122, 1, v6
	v_add_u32_e32 v208, v16, v18
	v_writelane_b32 v234, s1, 32
	v_cmp_lt_u32_e64 s[0:1], 18, v199
	v_lshlrev_b32_e32 v124, 1, v8
	v_lshlrev_b32_e32 v126, 1, v10
	v_writelane_b32 v234, s0, 33
	v_lshlrev_b32_e32 v128, 1, v12
	v_mov_b32_e32 v209, 0x7f
	v_writelane_b32 v234, s1, 34
	v_cmp_lt_u32_e64 s[0:1], 20, v199
	v_add_u32_e32 v210, s6, v9
	v_mov_b32_e32 v211, 0xff800000
	v_writelane_b32 v234, s0, 35
	v_mov_b32_e32 v212, 0x7f800000
	s_mov_b32 s38, 0
	v_writelane_b32 v234, s1, 36
	v_cmp_lt_u32_e64 s[0:1], 21, v199
	s_mov_b32 s44, 0x3fb8aa3b
	s_nop 0
	v_writelane_b32 v234, s0, 37
	s_nop 1
	v_writelane_b32 v234, s1, 38
	v_cmp_lt_u32_e64 s[0:1], 22, v199
	s_nop 1
	v_writelane_b32 v234, s0, 39
	s_nop 1
	v_writelane_b32 v234, s1, 40
	v_cmp_lt_u32_e64 s[0:1], 24, v199
	s_nop 1
	v_writelane_b32 v234, s0, 41
	s_nop 1
	v_writelane_b32 v234, s1, 42
	v_cmp_lt_u32_e64 s[0:1], 25, v199
	s_nop 1
	v_writelane_b32 v234, s0, 43
	s_nop 1
	v_writelane_b32 v234, s1, 44
	v_cmp_lt_u32_e64 s[0:1], 26, v199
	s_nop 1
	v_writelane_b32 v234, s0, 45
	s_nop 1
	v_writelane_b32 v234, s1, 46
	v_cmp_lt_u32_e64 s[0:1], 28, v199
	s_nop 1
	v_writelane_b32 v234, s0, 47
	s_nop 1
	v_writelane_b32 v234, s1, 48
	v_cmp_lt_u32_e64 s[0:1], 29, v199
	s_nop 1
	v_writelane_b32 v234, s0, 49
	s_nop 1
	v_writelane_b32 v234, s1, 50
	v_writelane_b32 v234, s96, 51
	s_nop 1
	v_writelane_b32 v234, s97, 52
	v_writelane_b32 v234, s78, 53
	s_nop 1
	v_writelane_b32 v234, s79, 54
	s_branch .LBB0_1270

.LBB0_1279:
	s_lshl_b32 s39, s45, 6
	s_and_b32 s8, s2, 3
	v_or_b32_e32 v130, s39, v154
	s_ashr_i32 s51, s50, 31
	s_lshl_b32 s2, s8, 2
	s_lshl_b64 s[46:47], s[50:51], 11
	v_ashrrev_i32_e32 v131, 31, v130
	s_add_i32 s3, s2, s21
	v_lshl_add_u64 v[0:1], s[46:47], 0, v[130:131]
	v_lshlrev_b64 v[2:3], 11, v[0:1]
	s_lshl_b32 s48, s3, 6
	v_lshl_add_u64 v[2:3], s[56:57], 0, v[2:3]
	s_ashr_i32 s49, s48, 31
	v_lshl_add_u64 v[2:3], s[48:49], 1, v[2:3]
	v_mov_b32_e32 v117, v32
	v_lshl_add_u64 v[2:3], v[2:3], 0, v[116:117]
	global_load_dwordx4 v[80:83], v[2:3], off
	global_load_dwordx4 v[84:87], v[2:3], off offset:32
	global_load_dwordx4 v[88:91], v[2:3], off offset:64
	global_load_dwordx4 v[92:95], v[2:3], off offset:96
	v_mov_b64_e32 v[2:3], s[76:77]
	v_mad_u64_u32 v[2:3], s[0:1], v0, s20, v[2:3]
	s_mul_i32 s0, s3, 3
	v_mad_i32_i24 v3, v1, s20, v3
	s_ashr_i32 s1, s0, 31
	v_lshl_add_u64 v[0:1], s[0:1], 2, v[2:3]
	global_load_dwordx3 v[104:106], v[0:1], off
	s_barrier
	s_cmp_eq_u32 s98, s8
	s_cbranch_scc1 .Lfa_btab_skip
	s_mov_b32 s98, s8
	s_and_saveexec_b64 s[0:1], s[22:23]
	s_cbranch_execz .LBB0_1284
	v_or_b32_e32 v0, s2, v196
	s_mov_b64 s[2:3], 0
	v_mov_b32_e32 v1, v205
	v_mov_b32_e32 v2, v107
	s_branch .LBB0_1282
.LBB0_1281:
	s_or_b64 exec, exec, s[6:7]
	s_movk_i32 s6, 0x33f
	ds_write_b32 v1, v3
	v_add_u32_e32 v3, 0x200, v2
	v_cmp_lt_i32_e32 vcc, s6, v2
	v_add_u32_e32 v1, 0x200, v1
	s_or_b64 s[2:3], vcc, s[2:3]
	v_mov_b32_e32 v2, v3
	s_andn2_b64 exec, exec, s[2:3]
	s_cbranch_execz .LBB0_1284

.Lfa_btab_skip:
	s_lshl_b32 s40, s8, 6
	s_lshl_b64 s[0:1], s[50:51], 16
	s_add_u32 s0, s73, s0
	s_addc_u32 s1, s19, s1
	s_lshl_b32 s2, s8, 7
	s_add_u32 s0, s0, s2
	s_addc_u32 s1, s1, 0
	v_mov_b32_e32 v121, v32
	v_lshl_add_u64 v[0:1], s[0:1], 0, v[120:121]
	s_mov_b64 s[0:1], 0x200000
	v_lshlrev_b64 v[4:5], 1, v[114:115]
	v_lshl_add_u64 v[2:3], v[0:1], 0, s[0:1]
	v_lshl_add_u64 v[6:7], v[0:1], 0, v[4:5]
	v_lshl_add_u64 v[4:5], v[2:3], 0, v[4:5]
	global_load_dwordx4 v[16:19], v[6:7], off
	global_load_dwordx4 v[20:23], v[4:5], off
	v_lshl_add_u64 v[0:1], v[0:1], 0, v[118:119]
	global_load_dwordx4 v[24:27], v[0:1], off
	v_lshl_add_u64 v[0:1], v[2:3], 0, v[118:119]
	global_load_dwordx4 v[28:31], v[0:1], off
	s_lshl_b32 s99, s40, 1
	s_mul_i32 s100, s50, 0x600000
	s_mul_hi_i32 s101, s50, 0x600000
	s_add_u32 s100, s24, s100
	s_addc_u32 s101, s25, s101
	s_add_u32 s100, s100, s99
	s_addc_u32 s101, s101, 0
	v_lshl_add_u64 v[252:253], s[100:101], 0, v[112:113]
	v_lshl_add_u64 v[252:253], v[252:253], 0, v[120:121]
	global_load_dwordx4 v[236:239], v[252:253], off offset:1024
	global_load_dwordx4 v[240:243], v[252:253], off offset:1536
	v_mov_b32_e32 v33, v32
	s_cmp_gt_i32 s45, 15
	v_mov_b32_e32 v34, v32
	v_mov_b32_e32 v35, v32
	v_mov_b32_e32 v36, v32
	v_mov_b32_e32 v37, v32
	v_mov_b32_e32 v38, v32
	v_mov_b32_e32 v39, v32
	v_mov_b32_e32 v40, v32
	v_mov_b32_e32 v41, v32
	v_mov_b32_e32 v42, v32
	v_mov_b32_e32 v43, v32
	v_mov_b32_e32 v44, v32
	v_mov_b32_e32 v45, v32
	v_mov_b32_e32 v46, v32
	v_mov_b32_e32 v47, v32
	v_mov_b64_e32 v[0:1], v[32:33]
	s_cselect_b64 s[30:31], -1, 0
	s_cmp_lt_i32 s45, 16
	s_mov_b32 s3, 0
	v_subrev_u32_e32 v66, 31, v130
	v_mov_b32_e32 v67, 0
	v_mov_b32_e32 v48, 0xff800000
	s_mov_b64 s[34:35], -1
	v_mov_b64_e32 v[2:3], v[34:35]
	v_mov_b64_e32 v[4:5], v[36:37]
	v_mov_b64_e32 v[6:7], v[38:39]
	v_mov_b64_e32 v[8:9], v[40:41]
	v_mov_b64_e32 v[10:11], v[42:43]
	v_mov_b64_e32 v[12:13], v[44:45]
	v_mov_b64_e32 v[14:15], v[46:47]
	s_cselect_b64 s[0:1], -1, 0
	s_waitcnt vmcnt(5)
	ds_write_b128 v195, v[16:19]
	s_waitcnt vmcnt(3)
	ds_write_b128 v195, v[24:27] offset:9216
	ds_write_b128 v195, v[20:23] offset:18432
	s_waitcnt vmcnt(2)
	ds_write_b128 v195, v[28:31] offset:27648
	v_mov_b64_e32 v[16:17], v[32:33]
	v_mov_b64_e32 v[18:19], v[34:35]
	v_mov_b64_e32 v[20:21], v[36:37]
	v_mov_b64_e32 v[22:23], v[38:39]
	v_mov_b64_e32 v[24:25], v[40:41]
	v_mov_b64_e32 v[26:27], v[42:43]
	v_mov_b64_e32 v[28:29], v[44:45]
	v_mov_b64_e32 v[30:31], v[46:47]
	s_waitcnt lgkmcnt(0)
	s_barrier
.LBB0_1285:
	s_mul_i32 s2, s3, 0x2400
	v_add_u32_e32 v33, s2, v156
	v_add_u32_e32 v42, v33, v157
	ds_read_b128 v[34:37], v42
	ds_read_b128 v[38:41], v42 offset:32
	v_add_u32_e32 v33, v33, v158
	v_mov_b32_e32 v68, v48
	s_lshl_b32 s3, s3, 6
	s_waitcnt lgkmcnt(1)
	v_mfma_f32_32x32x16_bf16 v[50:65], v[34:37], v[80:83], 0
	ds_read_b128 v[34:37], v42 offset:64
	s_waitcnt lgkmcnt(1)
	v_mfma_f32_32x32x16_bf16 v[50:65], v[38:41], v[84:87], v[50:65]
	s_waitcnt lgkmcnt(0)
	v_mfma_f32_32x32x16_bf16 v[50:65], v[34:37], v[88:91], v[50:65]
	ds_read_b128 v[34:37], v42 offset:96
	s_waitcnt lgkmcnt(0)
	v_mfma_f32_32x32x16_bf16 v[50:65], v[34:37], v[92:95], v[50:65]
	ds_read_b128 v[34:37], v33
	ds_read_b128 v[70:73], v33 offset:32
	s_waitcnt lgkmcnt(1)
	v_mfma_f32_32x32x16_bf16 v[34:49], v[34:37], v[80:83], 0
	s_waitcnt lgkmcnt(0)
	v_mfma_f32_32x32x16_bf16 v[34:49], v[70:73], v[84:87], v[34:49]
	ds_read_b128 v[70:73], v33 offset:64
	s_waitcnt lgkmcnt(0)
	v_mfma_f32_32x32x16_bf16 v[34:49], v[70:73], v[88:91], v[34:49]
	ds_read_b128 v[70:73], v33 offset:96
	v_subrev_u32_e32 v33, s3, v159
	v_lshl_add_u32 v33, v33, 4, v66
	v_med3_i32 v33, v33, -1, v209
	v_lshl_add_u32 v33, v33, 2, s69
	ds_read_b32 v69, v33 offset:256
	v_xad_u32 v33, s3, -1, v159
	v_lshl_add_u32 v33, v33, 4, v66
	v_med3_i32 v33, v33, -1, v209
	v_lshl_add_u32 v33, v33, 2, s69
	s_waitcnt lgkmcnt(1)
	v_mfma_f32_32x32x16_bf16 v[34:49], v[70:73], v[92:95], v[34:49]
	ds_read_b32 v70, v33 offset:256
	v_subrev_u32_e32 v33, s3, v160
	v_lshl_add_u32 v33, v33, 4, v66
	v_med3_i32 v33, v33, -1, v209
	v_lshl_add_u32 v33, v33, 2, s69
	ds_read_b32 v71, v33 offset:256
	v_subrev_u32_e32 v33, s3, v161
	v_lshl_add_u32 v33, v33, 4, v66
	v_med3_i32 v33, v33, -1, v209
	v_lshl_add_u32 v33, v33, 2, s69
	ds_read_b32 v72, v33 offset:256
	v_subrev_u32_e32 v33, s3, v162
	v_lshl_add_u32 v33, v33, 4, v66
	v_med3_i32 v33, v33, -1, v209
	v_lshl_add_u32 v33, v33, 2, s69
	ds_read_b32 v75, v33 offset:256
	v_subrev_u32_e32 v33, s3, v163
	v_lshl_add_u32 v33, v33, 4, v66
	v_med3_i32 v33, v33, -1, v209
	v_lshl_add_u32 v33, v33, 2, s69
	ds_read_b32 v73, v33 offset:256
	v_subrev_u32_e32 v33, s3, v164
	v_lshl_add_u32 v33, v33, 4, v66
	v_med3_i32 v33, v33, -1, v209
	v_lshl_add_u32 v33, v33, 2, s69
	ds_read_b32 v74, v33 offset:256
	v_subrev_u32_e32 v33, s3, v165
	v_lshl_add_u32 v33, v33, 4, v66
	v_med3_i32 v33, v33, -1, v209
	v_lshl_add_u32 v33, v33, 2, s69
	ds_read_b32 v76, v33 offset:256
	s_waitcnt lgkmcnt(7)
	v_fmac_f32_e32 v69, 0x3fb8aa3b, v50
	s_waitcnt lgkmcnt(6)
	v_fmac_f32_e32 v70, 0x3fb8aa3b, v51
	v_max3_f32 v33, v69, s70, v70
	s_waitcnt lgkmcnt(5)
	v_fmac_f32_e32 v71, 0x3fb8aa3b, v52
	s_waitcnt lgkmcnt(4)
	v_fmac_f32_e32 v72, 0x3fb8aa3b, v53
	v_max3_f32 v33, v33, v71, v72
	s_waitcnt lgkmcnt(3)
	v_fmac_f32_e32 v75, 0x3fb8aa3b, v54
	s_waitcnt lgkmcnt(2)
	v_fmac_f32_e32 v73, 0x3fb8aa3b, v55
	v_max3_f32 v33, v33, v75, v73
	s_waitcnt lgkmcnt(1)
	v_fmac_f32_e32 v74, 0x3fb8aa3b, v56
	s_waitcnt lgkmcnt(0)
	v_fmac_f32_e32 v76, 0x3fb8aa3b, v57
	v_max3_f32 v33, v33, v74, v76
	v_subrev_u32_e32 v50, s3, v166
	v_subrev_u32_e32 v51, s3, v167
	v_subrev_u32_e32 v53, s3, v169
	v_subrev_u32_e32 v55, s3, v171
	v_lshl_add_u32 v50, v50, 4, v66
	v_lshl_add_u32 v51, v51, 4, v66
	v_subrev_u32_e32 v52, s3, v168
	v_lshl_add_u32 v53, v53, 4, v66
	v_subrev_u32_e32 v54, s3, v170
	v_lshl_add_u32 v55, v55, 4, v66
	v_subrev_u32_e32 v56, s3, v172
	v_subrev_u32_e32 v57, s3, v173
	v_med3_i32 v50, v50, -1, v209
	v_med3_i32 v51, v51, -1, v209
	v_lshl_add_u32 v52, v52, 4, v66
	v_med3_i32 v53, v53, -1, v209
	v_lshl_add_u32 v54, v54, 4, v66
	v_med3_i32 v55, v55, -1, v209
	v_lshl_add_u32 v56, v56, 4, v66
	v_lshl_add_u32 v57, v57, 4, v66
	v_lshl_add_u32 v50, v50, 2, s69
	v_lshl_add_u32 v51, v51, 2, s69
	v_med3_i32 v52, v52, -1, v209
	v_lshl_add_u32 v53, v53, 2, s69
	v_med3_i32 v54, v54, -1, v209
	v_lshl_add_u32 v55, v55, 2, s69
	v_med3_i32 v56, v56, -1, v209
	v_med3_i32 v57, v57, -1, v209
	v_lshl_add_u32 v52, v52, 2, s69
	v_lshl_add_u32 v54, v54, 2, s69
	v_lshl_add_u32 v56, v56, 2, s69
	v_lshl_add_u32 v97, v57, 2, s69
	ds_read_b32 v96, v50 offset:256
	ds_read_b32 v79, v51 offset:256
	ds_read_b32 v78, v52 offset:256
	ds_read_b32 v77, v53 offset:256
	ds_read_b32 v57, v54 offset:256
	ds_read_b32 v55, v55 offset:256
	ds_read_b32 v53, v56 offset:256
	ds_read_b32 v51, v97 offset:256
	s_waitcnt lgkmcnt(7)
	v_fmac_f32_e32 v96, 0x3fb8aa3b, v58
	s_waitcnt lgkmcnt(6)
	v_fmac_f32_e32 v79, 0x3fb8aa3b, v59
	v_max3_f32 v33, v33, v96, v79
	s_waitcnt lgkmcnt(5)
	v_fmac_f32_e32 v78, 0x3fb8aa3b, v60
	s_waitcnt lgkmcnt(4)
	v_fmac_f32_e32 v77, 0x3fb8aa3b, v61
	v_max3_f32 v33, v33, v78, v77
	s_waitcnt lgkmcnt(3)
	v_fmac_f32_e32 v57, 0x3fb8aa3b, v62
	s_waitcnt lgkmcnt(2)
	v_fmac_f32_e32 v55, 0x3fb8aa3b, v63
	v_max3_f32 v33, v33, v57, v55
	s_waitcnt lgkmcnt(1)
	v_fmac_f32_e32 v53, 0x3fb8aa3b, v64
	s_waitcnt lgkmcnt(0)
	v_fmac_f32_e32 v51, 0x3fb8aa3b, v65
	v_max3_f32 v33, v33, v53, v51
	v_subrev_u32_e32 v58, s3, v178
	v_lshl_add_u32 v58, v58, 4, v66
	v_med3_i32 v58, v58, -1, v209
	v_lshl_add_u32 v61, v58, 2, s69
	v_subrev_u32_e32 v58, s3, v179
	v_lshl_add_u32 v58, v58, 4, v66
	v_med3_i32 v58, v58, -1, v209
	v_lshl_add_u32 v63, v58, 2, s69
	v_subrev_u32_e32 v58, s3, v180
	v_lshl_add_u32 v58, v58, 4, v66
	v_subrev_u32_e32 v50, s3, v174
	v_subrev_u32_e32 v52, s3, v175
	v_subrev_u32_e32 v54, s3, v176
	v_subrev_u32_e32 v56, s3, v177
	v_med3_i32 v58, v58, -1, v209
	v_lshl_add_u32 v50, v50, 4, v66
	v_lshl_add_u32 v52, v52, 4, v66
	v_lshl_add_u32 v54, v54, 4, v66
	v_lshl_add_u32 v56, v56, 4, v66
	v_lshl_add_u32 v64, v58, 2, s69
	v_subrev_u32_e32 v58, s3, v181
	v_med3_i32 v50, v50, -1, v209
	v_med3_i32 v52, v52, -1, v209
	v_med3_i32 v54, v54, -1, v209
	v_med3_i32 v56, v56, -1, v209
	v_lshl_add_u32 v58, v58, 4, v66
	v_lshl_add_u32 v50, v50, 2, s69
	v_lshl_add_u32 v52, v52, 2, s69
	v_lshl_add_u32 v54, v54, 2, s69
	v_lshl_add_u32 v56, v56, 2, s69
	v_med3_i32 v58, v58, -1, v209
	v_lshl_add_u32 v65, v58, 2, s69
	ds_read_b32 v62, v50 offset:256
	ds_read_b32 v60, v52 offset:256
	ds_read_b32 v59, v54 offset:256
	ds_read_b32 v58, v56 offset:256
	ds_read_b32 v56, v61 offset:256
	ds_read_b32 v54, v63 offset:256
	ds_read_b32 v52, v64 offset:256
	ds_read_b32 v50, v65 offset:256
	s_waitcnt lgkmcnt(7)
	v_fmac_f32_e32 v62, 0x3fb8aa3b, v34
	s_waitcnt lgkmcnt(6)
	v_fmac_f32_e32 v60, 0x3fb8aa3b, v35
	v_max3_f32 v33, v33, v62, v60
	s_waitcnt lgkmcnt(5)
	v_fmac_f32_e32 v59, 0x3fb8aa3b, v36
	s_waitcnt lgkmcnt(4)
	v_fmac_f32_e32 v58, 0x3fb8aa3b, v37
	v_max3_f32 v33, v33, v59, v58
	s_waitcnt lgkmcnt(3)
	v_fmac_f32_e32 v56, 0x3fb8aa3b, v38
	s_waitcnt lgkmcnt(2)
	v_fmac_f32_e32 v54, 0x3fb8aa3b, v39
	v_max3_f32 v33, v33, v56, v54
	s_waitcnt lgkmcnt(1)
	v_fmac_f32_e32 v52, 0x3fb8aa3b, v40
	s_waitcnt lgkmcnt(0)
	v_fmac_f32_e32 v50, 0x3fb8aa3b, v41
	v_max3_f32 v33, v33, v52, v50
	v_subrev_u32_e32 v39, s3, v187
	v_lshl_add_u32 v39, v39, 4, v66
	v_med3_i32 v39, v39, -1, v209
	v_lshl_add_u32 v63, v39, 2, s69
	v_subrev_u32_e32 v39, s3, v189
	v_lshl_add_u32 v39, v39, 4, v66
	v_subrev_u32_e32 v34, s3, v182
	v_subrev_u32_e32 v35, s3, v183
	v_subrev_u32_e32 v36, s3, v184
	v_subrev_u32_e32 v37, s3, v185
	v_subrev_u32_e32 v38, s3, v186
	v_med3_i32 v39, v39, -1, v209
	v_lshl_add_u32 v34, v34, 4, v66
	v_lshl_add_u32 v35, v35, 4, v66
	v_lshl_add_u32 v36, v36, 4, v66
	v_lshl_add_u32 v37, v37, 4, v66
	v_lshl_add_u32 v38, v38, 4, v66
	v_lshl_add_u32 v64, v39, 2, s69
	v_subrev_u32_e32 v39, s3, v190
	v_med3_i32 v34, v34, -1, v209
	v_med3_i32 v35, v35, -1, v209
	v_med3_i32 v36, v36, -1, v209
	v_med3_i32 v37, v37, -1, v209
	v_med3_i32 v38, v38, -1, v209
	v_lshl_add_u32 v39, v39, 4, v66
	v_lshl_add_u32 v34, v34, 2, s69
	v_lshl_add_u32 v35, v35, 2, s69
	v_lshl_add_u32 v36, v36, 2, s69
	v_lshl_add_u32 v37, v37, 2, s69
	v_lshl_add_u32 v38, v38, 2, s69
	v_med3_i32 v39, v39, -1, v209
	v_lshl_add_u32 v65, v39, 2, s69
	ds_read_b32 v61, v34 offset:256
	ds_read_b32 v41, v35 offset:256
	ds_read_b32 v40, v36 offset:256
	ds_read_b32 v39, v37 offset:256
	ds_read_b32 v38, v38 offset:256
	ds_read_b32 v37, v63 offset:256
	ds_read_b32 v36, v64 offset:256
	ds_read_b32 v35, v65 offset:256
	s_waitcnt lgkmcnt(7)
	v_fmac_f32_e32 v61, 0x3fb8aa3b, v42
	s_waitcnt lgkmcnt(6)
	v_fmac_f32_e32 v41, 0x3fb8aa3b, v43
	v_max3_f32 v33, v33, v61, v41
	s_waitcnt lgkmcnt(5)
	v_fmac_f32_e32 v40, 0x3fb8aa3b, v44
	s_waitcnt lgkmcnt(4)
	v_fmac_f32_e32 v39, 0x3fb8aa3b, v45
	v_max3_f32 v33, v33, v40, v39
	s_waitcnt lgkmcnt(3)
	v_fmac_f32_e32 v38, 0x3fb8aa3b, v46
	s_waitcnt lgkmcnt(2)
	v_fmac_f32_e32 v37, 0x3fb8aa3b, v47
	v_max3_f32 v33, v33, v38, v37
	s_waitcnt lgkmcnt(1)
	v_fmac_f32_e32 v36, 0x3fb8aa3b, v48
	s_waitcnt lgkmcnt(0)
	v_fmac_f32_e32 v35, 0x3fb8aa3b, v49
	v_max3_f32 v33, v33, v36, v35
	ds_bpermute_b32 v34, v155, v33
	s_waitcnt lgkmcnt(0)
	v_max3_f32 v48, v68, v33, v34
	v_cmp_neq_f32_e32 vcc, s70, v48
	s_nop 1
	v_cndmask_b32_e32 v33, 0, v48, vcc
	v_sub_f32_e32 v34, v68, v33
	v_exp_f32_e32 v34, v34
	s_nop 0
	v_cmp_neq_f32_e32 vcc, 1.0, v34
	s_cbranch_vccz .LBB0_1287
	v_pk_mul_f32 v[30:31], v[30:31], v[34:35] op_sel_hi:[1,0]
	v_pk_mul_f32 v[28:29], v[28:29], v[34:35] op_sel_hi:[1,0]
	v_pk_mul_f32 v[26:27], v[26:27], v[34:35] op_sel_hi:[1,0]
	v_pk_mul_f32 v[24:25], v[24:25], v[34:35] op_sel_hi:[1,0]
	v_pk_mul_f32 v[22:23], v[22:23], v[34:35] op_sel_hi:[1,0]
	v_pk_mul_f32 v[20:21], v[20:21], v[34:35] op_sel_hi:[1,0]
	v_pk_mul_f32 v[18:19], v[18:19], v[34:35] op_sel_hi:[1,0]
	v_pk_mul_f32 v[16:17], v[16:17], v[34:35] op_sel_hi:[1,0]
	v_pk_mul_f32 v[14:15], v[14:15], v[34:35] op_sel_hi:[1,0]
	v_pk_mul_f32 v[12:13], v[12:13], v[34:35] op_sel_hi:[1,0]
	v_pk_mul_f32 v[10:11], v[10:11], v[34:35] op_sel_hi:[1,0]
	v_pk_mul_f32 v[8:9], v[8:9], v[34:35] op_sel_hi:[1,0]
	v_pk_mul_f32 v[6:7], v[6:7], v[34:35] op_sel_hi:[1,0]
	v_pk_mul_f32 v[4:5], v[4:5], v[34:35] op_sel_hi:[1,0]
	v_pk_mul_f32 v[2:3], v[2:3], v[34:35] op_sel_hi:[1,0]
	v_pk_mul_f32 v[0:1], v[0:1], v[34:35] op_sel_hi:[1,0]

.LBB0_1291:
	s_mul_i32 s3, s2, 0x2400
	v_add_u32_e32 v8, s3, v156
	v_add_u32_e32 v9, v8, v157
	ds_read_b128 v[0:3], v9
	ds_read_b128 v[4:7], v9 offset:32
	s_lshl_b32 s2, s2, 6
	v_subrev_u32_e32 v10, s2, v159
	v_xad_u32 v11, s2, -1, v159
	s_waitcnt lgkmcnt(1)
	v_mfma_f32_32x32x16_bf16 v[16:31], v[0:3], v[80:83], 0
	ds_read_b128 v[0:3], v9 offset:64
	v_subrev_u32_e32 v12, s2, v160
	v_subrev_u32_e32 v13, s2, v161
	v_add_u32_e32 v8, v8, v158
	v_lshl_add_u32 v10, v10, 4, v66
	v_lshl_add_u32 v11, v11, 4, v66
	v_lshl_add_u32 v12, v12, 4, v66
	s_waitcnt lgkmcnt(1)
	v_mfma_f32_32x32x16_bf16 v[16:31], v[4:7], v[84:87], v[16:31]
	ds_read_b128 v[4:7], v9 offset:96
	v_lshl_add_u32 v9, v13, 4, v66
	v_subrev_u32_e32 v14, s2, v162
	v_lshl_add_u32 v48, v14, 4, v66
	v_subrev_u32_e32 v54, s2, v164
	v_subrev_u32_e32 v53, s2, v163
	v_lshl_add_u32 v53, v53, 4, v66
	s_waitcnt lgkmcnt(1)
	v_mfma_f32_32x32x16_bf16 v[16:31], v[0:3], v[88:91], v[16:31]
	ds_read_b128 v[0:3], v8
	ds_read_b128 v[36:39], v8 offset:32
	ds_read_b128 v[40:43], v8 offset:64
	ds_read_b128 v[44:47], v8 offset:96
	v_med3_i32 v8, v10, -1, v209
	v_lshl_add_u32 v49, v8, 2, s69
	v_med3_i32 v48, v48, -1, v209
	v_med3_i32 v53, v53, -1, v209
	v_lshl_add_u32 v48, v48, 2, s69
	v_lshl_add_u32 v53, v53, 2, s69
	s_waitcnt lgkmcnt(4)
	v_mfma_f32_32x32x16_bf16 v[16:31], v[4:7], v[92:95], v[16:31]
	v_med3_i32 v4, v11, -1, v209
	v_med3_i32 v5, v12, -1, v209
	v_med3_i32 v6, v9, -1, v209
	v_lshl_add_u32 v50, v4, 2, s69
	v_lshl_add_u32 v51, v5, 2, s69
	v_lshl_add_u32 v52, v6, 2, s69
	s_waitcnt lgkmcnt(3)
	v_mfma_f32_32x32x16_bf16 v[0:15], v[0:3], v[80:83], 0
	s_waitcnt lgkmcnt(2)
	v_mfma_f32_32x32x16_bf16 v[0:15], v[36:39], v[84:87], v[0:15]
	v_subrev_u32_e32 v37, s2, v165
	v_lshl_add_u32 v36, v54, 4, v66
	v_lshl_add_u32 v37, v37, 4, v66
	v_med3_i32 v36, v36, -1, v209
	v_med3_i32 v37, v37, -1, v209
	v_lshl_add_u32 v36, v36, 2, s69
	v_lshl_add_u32 v37, v37, 2, s69
	s_waitcnt lgkmcnt(1)
	v_mfma_f32_32x32x16_bf16 v[0:15], v[40:43], v[88:91], v[0:15]
	ds_read_b32 v38, v49 offset:256
	ds_read_b32 v39, v50 offset:256
	ds_read_b32 v40, v51 offset:256
	ds_read_b32 v41, v52 offset:256
	ds_read_b32 v42, v48 offset:256
	ds_read_b32 v43, v53 offset:256
	ds_read_b32 v36, v36 offset:256
	ds_read_b32 v37, v37 offset:256
	s_waitcnt lgkmcnt(8)
	v_mfma_f32_32x32x16_bf16 v[0:15], v[44:47], v[92:95], v[0:15]
	s_waitcnt lgkmcnt(7)
	v_fmac_f32_e32 v38, 0x3fb8aa3b, v16
	s_waitcnt lgkmcnt(6)
	v_fmac_f32_e32 v39, 0x3fb8aa3b, v17
	s_waitcnt lgkmcnt(5)
	v_fmac_f32_e32 v40, 0x3fb8aa3b, v18
	s_waitcnt lgkmcnt(4)
	v_fmac_f32_e32 v41, 0x3fb8aa3b, v19
	s_waitcnt lgkmcnt(3)
	v_fmac_f32_e32 v42, 0x3fb8aa3b, v20
	s_waitcnt lgkmcnt(2)
	v_fmac_f32_e32 v43, 0x3fb8aa3b, v21
	s_waitcnt lgkmcnt(1)
	v_fmac_f32_e32 v36, 0x3fb8aa3b, v22
	s_waitcnt lgkmcnt(0)
	v_fmac_f32_e32 v37, 0x3fb8aa3b, v23
	v_subrev_u32_e32 v16, s2, v166
	v_subrev_u32_e32 v17, s2, v167
	v_subrev_u32_e32 v18, s2, v168
	v_subrev_u32_e32 v19, s2, v169
	v_subrev_u32_e32 v20, s2, v170
	v_subrev_u32_e32 v21, s2, v171
	v_subrev_u32_e32 v22, s2, v172
	v_subrev_u32_e32 v23, s2, v173
	v_lshl_add_u32 v16, v16, 4, v66
	v_lshl_add_u32 v17, v17, 4, v66
	v_lshl_add_u32 v18, v18, 4, v66
	v_lshl_add_u32 v19, v19, 4, v66
	v_lshl_add_u32 v20, v20, 4, v66
	v_lshl_add_u32 v21, v21, 4, v66
	v_lshl_add_u32 v22, v22, 4, v66
	v_lshl_add_u32 v23, v23, 4, v66
	v_med3_i32 v16, v16, -1, v209
	v_med3_i32 v17, v17, -1, v209
	v_med3_i32 v18, v18, -1, v209
	v_med3_i32 v19, v19, -1, v209
	v_med3_i32 v20, v20, -1, v209
	v_med3_i32 v21, v21, -1, v209
	v_med3_i32 v22, v22, -1, v209
	v_med3_i32 v23, v23, -1, v209
	v_lshl_add_u32 v16, v16, 2, s69
	v_lshl_add_u32 v17, v17, 2, s69
	v_lshl_add_u32 v18, v18, 2, s69
	v_lshl_add_u32 v19, v19, 2, s69
	v_lshl_add_u32 v20, v20, 2, s69
	v_lshl_add_u32 v21, v21, 2, s69
	v_lshl_add_u32 v22, v22, 2, s69
	v_lshl_add_u32 v23, v23, 2, s69
	ds_read_b32 v16, v16 offset:256
	ds_read_b32 v17, v17 offset:256
	ds_read_b32 v18, v18 offset:256
	ds_read_b32 v19, v19 offset:256
	ds_read_b32 v20, v20 offset:256
	ds_read_b32 v21, v21 offset:256
	ds_read_b32 v22, v22 offset:256
	ds_read_b32 v23, v23 offset:256
	s_waitcnt lgkmcnt(7)
	v_fmac_f32_e32 v16, 0x3fb8aa3b, v24
	s_waitcnt lgkmcnt(6)
	v_fmac_f32_e32 v17, 0x3fb8aa3b, v25
	s_waitcnt lgkmcnt(5)
	v_fmac_f32_e32 v18, 0x3fb8aa3b, v26
	s_waitcnt lgkmcnt(4)
	v_fmac_f32_e32 v19, 0x3fb8aa3b, v27
	s_waitcnt lgkmcnt(3)
	v_fmac_f32_e32 v20, 0x3fb8aa3b, v28
	s_waitcnt lgkmcnt(2)
	v_fmac_f32_e32 v21, 0x3fb8aa3b, v29
	s_waitcnt lgkmcnt(1)
	v_fmac_f32_e32 v22, 0x3fb8aa3b, v30
	s_waitcnt lgkmcnt(0)
	v_fmac_f32_e32 v23, 0x3fb8aa3b, v31
	v_subrev_u32_e32 v24, s2, v174
	v_subrev_u32_e32 v25, s2, v175
	v_subrev_u32_e32 v26, s2, v176
	v_subrev_u32_e32 v27, s2, v177
	v_subrev_u32_e32 v28, s2, v178
	v_subrev_u32_e32 v29, s2, v179
	v_subrev_u32_e32 v30, s2, v180
	v_subrev_u32_e32 v31, s2, v181
	v_lshl_add_u32 v24, v24, 4, v66
	v_lshl_add_u32 v25, v25, 4, v66
	v_lshl_add_u32 v26, v26, 4, v66
	v_lshl_add_u32 v27, v27, 4, v66
	v_lshl_add_u32 v28, v28, 4, v66
	v_lshl_add_u32 v29, v29, 4, v66
	v_lshl_add_u32 v30, v30, 4, v66
	v_lshl_add_u32 v31, v31, 4, v66
	v_med3_i32 v24, v24, -1, v209
	v_med3_i32 v25, v25, -1, v209
	v_med3_i32 v26, v26, -1, v209
	v_med3_i32 v27, v27, -1, v209
	v_med3_i32 v28, v28, -1, v209
	v_med3_i32 v29, v29, -1, v209
	v_med3_i32 v30, v30, -1, v209
	v_med3_i32 v31, v31, -1, v209
	v_lshl_add_u32 v24, v24, 2, s69
	v_lshl_add_u32 v25, v25, 2, s69
	v_lshl_add_u32 v26, v26, 2, s69
	v_lshl_add_u32 v27, v27, 2, s69
	v_lshl_add_u32 v28, v28, 2, s69
	v_lshl_add_u32 v29, v29, 2, s69
	v_lshl_add_u32 v30, v30, 2, s69
	v_lshl_add_u32 v31, v31, 2, s69
	ds_read_b32 v24, v24 offset:256
	ds_read_b32 v25, v25 offset:256
	ds_read_b32 v26, v26 offset:256
	ds_read_b32 v27, v27 offset:256
	ds_read_b32 v28, v28 offset:256
	ds_read_b32 v29, v29 offset:256
	ds_read_b32 v30, v30 offset:256
	ds_read_b32 v31, v31 offset:256
	s_waitcnt lgkmcnt(7)
	v_fmac_f32_e32 v24, 0x3fb8aa3b, v0
	s_waitcnt lgkmcnt(6)
	v_fmac_f32_e32 v25, 0x3fb8aa3b, v1
	s_waitcnt lgkmcnt(5)
	v_fmac_f32_e32 v26, 0x3fb8aa3b, v2
	s_waitcnt lgkmcnt(4)
	v_fmac_f32_e32 v27, 0x3fb8aa3b, v3
	s_waitcnt lgkmcnt(3)
	v_fmac_f32_e32 v28, 0x3fb8aa3b, v4
	s_waitcnt lgkmcnt(2)
	v_fmac_f32_e32 v29, 0x3fb8aa3b, v5
	s_waitcnt lgkmcnt(1)
	v_fmac_f32_e32 v30, 0x3fb8aa3b, v6
	s_waitcnt lgkmcnt(0)
	v_fmac_f32_e32 v31, 0x3fb8aa3b, v7
	v_subrev_u32_e32 v0, s2, v182
	v_subrev_u32_e32 v1, s2, v183
	v_subrev_u32_e32 v2, s2, v184
	v_subrev_u32_e32 v3, s2, v185
	v_subrev_u32_e32 v4, s2, v186
	v_subrev_u32_e32 v5, s2, v187
	v_subrev_u32_e32 v6, s2, v189
	v_subrev_u32_e32 v7, s2, v190
	v_lshl_add_u32 v0, v0, 4, v66
	v_lshl_add_u32 v1, v1, 4, v66
	v_lshl_add_u32 v2, v2, 4, v66
	v_lshl_add_u32 v3, v3, 4, v66
	v_lshl_add_u32 v4, v4, 4, v66
	v_lshl_add_u32 v5, v5, 4, v66
	v_lshl_add_u32 v6, v6, 4, v66
	v_lshl_add_u32 v7, v7, 4, v66
	v_med3_i32 v0, v0, -1, v209
	v_med3_i32 v1, v1, -1, v209
	v_med3_i32 v2, v2, -1, v209
	v_med3_i32 v3, v3, -1, v209
	v_med3_i32 v4, v4, -1, v209
	v_med3_i32 v5, v5, -1, v209
	v_med3_i32 v6, v6, -1, v209
	v_med3_i32 v7, v7, -1, v209
	v_lshl_add_u32 v0, v0, 2, s69
	v_lshl_add_u32 v1, v1, 2, s69
	v_lshl_add_u32 v2, v2, 2, s69
	v_lshl_add_u32 v3, v3, 2, s69
	v_lshl_add_u32 v4, v4, 2, s69
	v_lshl_add_u32 v5, v5, 2, s69
	v_lshl_add_u32 v6, v6, 2, s69
	v_lshl_add_u32 v7, v7, 2, s69
	ds_read_b32 v0, v0 offset:256
	ds_read_b32 v1, v1 offset:256
	ds_read_b32 v2, v2 offset:256
	ds_read_b32 v3, v3 offset:256
	ds_read_b32 v4, v4 offset:256
	ds_read_b32 v5, v5 offset:256
	ds_read_b32 v6, v6 offset:256
	ds_read_b32 v7, v7 offset:256
	s_waitcnt lgkmcnt(7)
	v_fmac_f32_e32 v0, 0x3fb8aa3b, v8
	s_waitcnt lgkmcnt(6)
	v_fmac_f32_e32 v1, 0x3fb8aa3b, v9
	s_waitcnt lgkmcnt(5)
	v_fmac_f32_e32 v2, 0x3fb8aa3b, v10
	s_waitcnt lgkmcnt(4)
	v_fmac_f32_e32 v3, 0x3fb8aa3b, v11
	s_waitcnt lgkmcnt(3)
	v_fmac_f32_e32 v4, 0x3fb8aa3b, v12
	s_waitcnt lgkmcnt(2)
	v_fmac_f32_e32 v5, 0x3fb8aa3b, v13
	s_waitcnt lgkmcnt(1)
	v_fmac_f32_e32 v6, 0x3fb8aa3b, v14
	s_waitcnt lgkmcnt(0)
	v_fmac_f32_e32 v7, 0x3fb8aa3b, v15
	v_sub_f32_e32 v12, v41, v33
	v_exp_f32_e32 v12, v12
	v_sub_f32_e32 v10, v39, v33
	v_sub_f32_e32 v15, v36, v33
	v_sub_f32_e32 v36, v37, v33
	v_sub_f32_e32 v9, v38, v33
	v_sub_f32_e32 v14, v43, v33
	v_sub_f32_e32 v17, v17, v33
	v_sub_f32_e32 v19, v19, v33
	v_sub_f32_e32 v23, v23, v33
	v_sub_f32_e32 v27, v27, v33
	v_sub_f32_e32 v31, v31, v33
	v_sub_f32_e32 v1, v1, v33
	v_sub_f32_e32 v3, v3, v33
	v_exp_f32_e32 v10, v10
	v_exp_f32_e32 v36, v36
	v_sub_f32_e32 v11, v40, v33
	v_sub_f32_e32 v13, v42, v33
	v_sub_f32_e32 v16, v16, v33
	v_sub_f32_e32 v18, v18, v33
	v_sub_f32_e32 v0, v0, v33
	v_sub_f32_e32 v2, v2, v33
	v_sub_f32_e32 v7, v7, v33
	v_exp_f32_e32 v9, v9
	v_exp_f32_e32 v14, v14
	v_exp_f32_e32 v17, v17
	v_exp_f32_e32 v19, v19
	v_exp_f32_e32 v23, v23
	v_exp_f32_e32 v27, v27
	v_exp_f32_e32 v31, v31
	v_exp_f32_e32 v1, v1
	v_exp_f32_e32 v3, v3
	v_mul_f32_e32 v12, v34, v12
	v_exp_f32_e32 v11, v11
	v_exp_f32_e32 v13, v13
	v_exp_f32_e32 v15, v15
	v_exp_f32_e32 v16, v16
	v_exp_f32_e32 v18, v18
	v_exp_f32_e32 v0, v0
	v_exp_f32_e32 v2, v2
	v_exp_f32_e32 v7, v7
	ds_bpermute_b32 v37, v155, v12
	v_sub_f32_e32 v21, v21, v33
	v_sub_f32_e32 v25, v25, v33
	v_sub_f32_e32 v29, v29, v33
	v_sub_f32_e32 v5, v5, v33
	v_mul_f32_e32 v10, v34, v10
	v_mul_f32_e32 v36, v34, v36
	v_sub_f32_e32 v20, v20, v33
	v_sub_f32_e32 v22, v22, v33
	v_sub_f32_e32 v24, v24, v33
	v_sub_f32_e32 v26, v26, v33
	v_sub_f32_e32 v28, v28, v33
	v_sub_f32_e32 v30, v30, v33
	v_sub_f32_e32 v4, v4, v33
	v_exp_f32_e32 v21, v21
	v_exp_f32_e32 v25, v25
	v_exp_f32_e32 v29, v29
	v_exp_f32_e32 v5, v5
	v_mul_f32_e32 v14, v34, v14
	v_mul_f32_e32 v17, v34, v17
	v_mul_f32_e32 v19, v34, v19
	v_mul_f32_e32 v23, v34, v23
	v_mul_f32_e32 v27, v34, v27
	v_mul_f32_e32 v31, v34, v31
	v_mul_f32_e32 v1, v34, v1
	v_mul_f32_e32 v3, v34, v3
	v_fmac_f32_e32 v10, v34, v9
	ds_bpermute_b32 v9, v155, v36
	v_sub_f32_e32 v6, v6, v33
	v_exp_f32_e32 v20, v20
	v_exp_f32_e32 v22, v22
	v_exp_f32_e32 v24, v24
	v_exp_f32_e32 v26, v26
	v_exp_f32_e32 v28, v28
	v_exp_f32_e32 v30, v30
	v_exp_f32_e32 v4, v4
	v_mul_f32_e32 v7, v34, v7
	v_fmac_f32_e32 v12, v34, v11
	v_fmac_f32_e32 v14, v34, v13
	v_fmac_f32_e32 v36, v34, v15
	ds_bpermute_b32 v11, v155, v19
	v_fmac_f32_e32 v17, v34, v16
	v_fmac_f32_e32 v19, v34, v18
	ds_bpermute_b32 v13, v155, v23
	ds_bpermute_b32 v15, v155, v27
	ds_bpermute_b32 v16, v155, v31
	ds_bpermute_b32 v18, v155, v3
	v_fmac_f32_e32 v1, v34, v0
	v_fmac_f32_e32 v3, v34, v2
	v_exp_f32_e32 v6, v6
	v_add_f32_e32 v1, v1, v3
	s_waitcnt lgkmcnt(6)
	v_cndmask_b32_e64 v3, v37, v35, s[4:5]
	ds_bpermute_b32 v35, v155, v7
	v_mul_f32_e32 v21, v34, v21
	v_mul_f32_e32 v25, v34, v25
	v_mul_f32_e32 v29, v34, v29
	v_mul_f32_e32 v5, v34, v5
	v_add_u32_e32 v8, s2, v110
	v_fmac_f32_e32 v21, v34, v20
	v_fmac_f32_e32 v23, v34, v22
	v_fmac_f32_e32 v25, v34, v24
	v_fmac_f32_e32 v27, v34, v26
	v_fmac_f32_e32 v29, v34, v28
	v_fmac_f32_e32 v31, v34, v30
	v_fmac_f32_e32 v5, v34, v4
	v_add_f32_e32 v0, v10, v12
	v_add_f32_e32 v2, v14, v36
	v_add_f32_e32 v4, v17, v19
	s_waitcnt lgkmcnt(6)
	v_cndmask_b32_e64 v17, v9, v37, s[4:5]
	v_add_u32_e32 v8, 0x9000, v8
	v_add_f32_e32 v10, v21, v23
	v_add_f32_e32 v12, v25, v27
	v_add_f32_e32 v14, v29, v31
	s_waitcnt lgkmcnt(5)
	v_cndmask_b32_e64 v9, v11, v9, s[4:5]
	s_waitcnt lgkmcnt(4)
	v_cndmask_b32_e64 v11, v13, v11, s[4:5]
	s_waitcnt lgkmcnt(3)
	v_cndmask_b32_e64 v13, v15, v13, s[4:5]
	s_waitcnt lgkmcnt(2)
	v_cndmask_b32_e64 v15, v16, v15, s[4:5]
	v_fmac_f32_e32 v7, v34, v6
	v_add_f32_e32 v0, v0, v3
	v_add_f32_e32 v2, v2, v17
	s_waitcnt lgkmcnt(1)
	v_cndmask_b32_e64 v16, v18, v16, s[4:5]
	v_add_f32_e32 v3, v4, v9
	v_add_f32_e32 v4, v10, v11
	v_add_f32_e32 v6, v12, v13
	v_add_f32_e32 v9, v14, v15
	v_add_f32_e32 v5, v5, v7
	ds_write2_b32 v8, v0, v2 offset1:2
	ds_write2_b32 v8, v3, v4 offset0:4 offset1:6
	ds_write2_b32 v8, v6, v9 offset0:8 offset1:10
	s_waitcnt lgkmcnt(3)
	v_cndmask_b32_e64 v0, v35, v18, s[4:5]
	s_mov_b32 s2, 1
	s_and_b64 vcc, exec, s[30:31]
	s_mov_b64 s[30:31], 0
	v_add_f32_e32 v1, v1, v16
	v_add_f32_e32 v0, v5, v0
	ds_write2_b32 v8, v1, v0 offset0:12 offset1:14
	s_cbranch_vccnz .LBB0_1291

.LBB0_1449:
	s_add_i32 s6, s45, 1
	s_max_i32 s2, s45, 8
	s_lshl_b32 s0, s6, 1
	s_sub_i32 s8, s0, s2
	s_mul_i32 s1, s50, 0x600000
	s_mul_hi_i32 s0, s50, 0x600000
	s_add_u32 s1, s24, s1
	s_addc_u32 s3, s25, s0
	s_lshl_b32 s0, s40, 1
	s_add_u32 s0, s1, s0
	s_addc_u32 s1, s3, 0
	v_lshl_add_u64 v[0:1], s[0:1], 0, v[112:113]
	v_mov_b32_e32 v121, v32
	v_lshl_add_u64 v[0:1], v[0:1], 0, v[120:121]
	s_waitcnt lgkmcnt(0)
	s_barrier
	ds_read_b32 v104, v194
	s_cmp_lt_i32 s8, -7
	s_waitcnt vmcnt(1)
	ds_write_b128 v195, v[236:239]
	s_waitcnt vmcnt(0)
	ds_write_b128 v195, v[240:243] offset:18432
	s_waitcnt lgkmcnt(0)
	s_barrier
	s_cbranch_scc1 .LBB0_1268
	v_lshl_add_u64 v[132:133], s[0:1], 0, v[120:121]
	s_add_i32 s0, s2, -8
	s_not_b32 s1, s45
	s_add_i32 s7, s0, s1
	s_lshl_b32 s1, s45, 1
	v_mov_b32_e32 v46, v32
	v_mov_b32_e32 v47, v32
	s_sub_i32 s9, s1, s2
	v_mov_b32_e32 v33, v32
	v_mov_b32_e32 v34, v32
	v_mov_b32_e32 v35, v32
	v_mov_b32_e32 v36, v32
	v_mov_b32_e32 v37, v32
	v_mov_b32_e32 v38, v32
	v_mov_b32_e32 v39, v32
	v_mov_b32_e32 v40, v32
	v_mov_b32_e32 v41, v32
	v_mov_b32_e32 v42, v32
	v_mov_b32_e32 v43, v32
	v_mov_b32_e32 v44, v32
	v_mov_b32_e32 v45, v32
	v_mov_b64_e32 v[78:79], v[46:47]
	v_mov_b64_e32 v[62:63], v[46:47]
	v_sub_u32_e32 v117, v130, v152
	s_add_i32 s8, s8, 7
	s_add_i32 s9, s9, 10
	s_sub_i32 s28, s0, s45
	s_mov_b32 s2, 0
	v_mov_b32_e32 v121, 0
	v_mov_b32_e32 v123, 0xff800000
	v_mov_b64_e32 v[76:77], v[44:45]
	v_mov_b64_e32 v[74:75], v[42:43]
	v_mov_b64_e32 v[72:73], v[40:41]
	v_mov_b64_e32 v[70:71], v[38:39]
	v_mov_b64_e32 v[68:69], v[36:37]
	v_mov_b64_e32 v[66:67], v[34:35]
	v_mov_b64_e32 v[64:65], v[32:33]
	v_mov_b64_e32 v[60:61], v[44:45]
	v_mov_b64_e32 v[58:59], v[42:43]
	v_mov_b64_e32 v[56:57], v[40:41]
	v_mov_b64_e32 v[54:55], v[38:39]
	v_mov_b64_e32 v[52:53], v[36:37]
	v_mov_b64_e32 v[50:51], v[34:35]
	v_mov_b64_e32 v[48:49], v[32:33]

.LBB0_1455:
	s_and_b32 s36, s2, 1
	s_cmp_gt_i32 s2, s45
	s_cselect_b64 s[0:1], -1, 0
	s_and_b64 s[34:35], s[0:1], exec
	s_cselect_b32 s40, s7, 0
	s_add_i32 s40, s40, s2
	v_readfirstlane_b32 s3, v117
	s_lshl_b32 s50, s40, 6
	s_add_i32 s2, s3, 31
	s_cmp_lt_i32 s2, s50
	s_cbranch_scc1 .LBB0_1470
	s_sub_i32 s3, s3, s50
	s_sub_i32 s3, s3, 63
	s_cmpk_gt_i32 s3, 0x1ff
	s_cselect_b64 s[34:35], -1, 0
	s_and_b64 s[34:35], s[0:1], s[34:35]
	s_and_b64 vcc, exec, s[34:35]
	s_cbranch_vccnz .LBB0_1470
	s_mul_i32 s37, s36, 0x2400
	v_add_u32_e32 v20, s37, v156
	v_add_u32_e32 v21, v20, v157
	v_add_u32_e32 v33, v20, v158
	ds_read_b128 v[134:137], v21
	ds_read_b128 v[138:141], v21 offset:32
	ds_read_b128 v[142:145], v21 offset:64
	ds_read_b128 v[146:149], v21 offset:96
	ds_read_b128 v[236:239], v33
	ds_read_b128 v[240:243], v33 offset:32
	ds_read_b128 v[244:247], v33 offset:64
	ds_read_b128 v[248:251], v33 offset:96
	s_cmpk_gt_i32 s3, 0x70
	s_cselect_b64 s[34:35], -1, 0
	s_and_b64 s[52:53], s[0:1], s[34:35]
	s_sub_i32 s51, s2, s50
	s_cmpk_lt_i32 s51, 0x200
	s_cselect_b64 s[2:3], -1, 0
	s_waitcnt lgkmcnt(7)
	v_mfma_f32_32x32x16_bf16 v[0:15], v[134:137], v[80:83], 0
	s_waitcnt lgkmcnt(6)
	v_mfma_f32_32x32x16_bf16 v[0:15], v[138:141], v[84:87], v[0:15]
	s_waitcnt lgkmcnt(5)
	v_mfma_f32_32x32x16_bf16 v[0:15], v[142:145], v[88:91], v[0:15]
	s_waitcnt lgkmcnt(4)
	v_mfma_f32_32x32x16_bf16 v[0:15], v[146:149], v[92:95], v[0:15]
	s_waitcnt lgkmcnt(3)
	v_mfma_f32_32x32x16_bf16 v[16:31], v[236:239], v[80:83], 0
	s_waitcnt lgkmcnt(2)
	v_mfma_f32_32x32x16_bf16 v[16:31], v[240:243], v[84:87], v[16:31]
	s_waitcnt lgkmcnt(1)
	v_mfma_f32_32x32x16_bf16 v[16:31], v[244:247], v[88:91], v[16:31]
	v_cndmask_b32_e64 v33, 0, 1, s[34:35]
	s_waitcnt lgkmcnt(0)
	v_mfma_f32_32x32x16_bf16 v[16:31], v[248:251], v[92:95], v[16:31]
	v_cndmask_b32_e64 v34, 0, 1, s[2:3]
	s_and_b64 s[2:3], s[52:53], exec
	v_readfirstlane_b32 s2, v34
	v_readfirstlane_b32 s3, v33
	s_cselect_b32 s2, s2, s3
	s_bitcmp1_b32 s2, 0
	s_cselect_b64 s[34:35], -1, 0
	s_xor_b64 s[34:35], s[34:35], -1
	s_mov_b64 s[2:3], -1
	s_and_b64 vcc, exec, s[34:35]
	s_nop 1
	s_cbranch_vccz .Lfa_fast
	v_or_b32_e32 v125, s50, v153
	s_cmpk_lt_i32 s51, 0x110
	v_sub_u32_e32 v33, v130, v125
	s_cbranch_scc1 .LBB0_1460
	v_cmp_lt_i32_e32 vcc, s67, v33
	s_and_b64 vcc, s[0:1], vcc
	v_xad_u32 v36, v125, -1, v130
	v_cndmask_b32_e32 v35, 0, v211, vcc
	v_cmp_lt_i32_e32 vcc, s67, v36
	v_or_b32_e32 v38, 2, v125
	s_and_b64 vcc, s[0:1], vcc
	v_sub_u32_e32 v38, v130, v38
	v_med3_i32 v37, v36, -1, v209
	v_cndmask_b32_e32 v36, 0, v211, vcc
	v_med3_i32 v39, v38, -1, v209
	v_cmp_lt_i32_e32 vcc, s67, v38
	v_or_b32_e32 v38, 3, v125
	s_and_b64 vcc, s[0:1], vcc
	v_sub_u32_e32 v38, v130, v38
	v_cndmask_b32_e32 v40, 0, v211, vcc
	v_med3_i32 v41, v38, -1, v209
	v_cmp_lt_i32_e32 vcc, s67, v38
	v_or_b32_e32 v38, 8, v125
	s_and_b64 vcc, s[0:1], vcc
	v_sub_u32_e32 v38, v130, v38
	v_cndmask_b32_e32 v42, 0, v211, vcc
	v_med3_i32 v43, v38, -1, v209
	v_cmp_lt_i32_e32 vcc, s67, v38
	v_or_b32_e32 v38, 9, v125
	s_and_b64 vcc, s[0:1], vcc
	v_sub_u32_e32 v38, v130, v38
	v_cndmask_b32_e32 v44, 0, v211, vcc
	v_med3_i32 v45, v38, -1, v209
	v_cmp_lt_i32_e32 vcc, s67, v38
	v_or_b32_e32 v38, 10, v125
	s_and_b64 vcc, s[0:1], vcc
	v_sub_u32_e32 v38, v130, v38
	v_cndmask_b32_e32 v46, 0, v211, vcc
	v_med3_i32 v47, v38, -1, v209
	v_cmp_lt_i32_e32 vcc, s67, v38
	v_or_b32_e32 v38, 11, v125
	v_sub_u32_e32 v38, v130, v38
	v_med3_i32 v34, v33, -1, v209
	v_med3_i32 v127, v38, -1, v209
	v_lshl_add_u32 v34, v34, 2, s69
	v_lshl_add_u32 v37, v37, 2, s69
	v_lshl_add_u32 v41, v41, 2, s69
	v_lshl_add_u32 v43, v43, 2, s69
	v_lshl_add_u32 v45, v45, 2, s69
	v_lshl_add_u32 v47, v47, 2, s69
	v_lshl_add_u32 v127, v127, 2, s69
	v_lshl_add_u32 v39, v39, 2, s69
	ds_read_b32 v34, v34 offset:256
	ds_read_b32 v37, v37 offset:256
	ds_read_b32 v129, v39 offset:256
	ds_read_b32 v41, v41 offset:256
	ds_read_b32 v43, v43 offset:256
	ds_read_b32 v45, v45 offset:256
	ds_read_b32 v47, v47 offset:256
	ds_read_b32 v127, v127 offset:256
	s_and_b64 vcc, s[0:1], vcc
	v_cndmask_b32_e32 v131, 0, v211, vcc
	v_cmp_lt_i32_e32 vcc, s67, v38
	s_and_b64 vcc, s[0:1], vcc
	s_nop 0
	v_cndmask_b32_e32 v134, 0, v211, vcc
	s_waitcnt lgkmcnt(7)
	v_fmac_f32_e32 v34, 0x3fb8aa3b, v0
	s_waitcnt lgkmcnt(6)
	v_fmac_f32_e32 v37, 0x3fb8aa3b, v1
	v_add_f32_e32 v38, v35, v34
	v_add_f32_e32 v39, v36, v37
	s_waitcnt lgkmcnt(5)
	v_fmac_f32_e32 v129, 0x3fb8aa3b, v2
	s_waitcnt lgkmcnt(4)
	v_fmac_f32_e32 v41, 0x3fb8aa3b, v3
	v_max3_f32 v34, v38, s70, v39
	v_add_f32_e32 v36, v40, v129
	v_add_f32_e32 v37, v42, v41
	s_waitcnt lgkmcnt(3)
	v_fmac_f32_e32 v43, 0x3fb8aa3b, v4
	s_waitcnt lgkmcnt(2)
	v_fmac_f32_e32 v45, 0x3fb8aa3b, v5
	v_max3_f32 v34, v34, v36, v37
	v_add_f32_e32 v40, v44, v43
	v_add_f32_e32 v41, v46, v45
	s_waitcnt lgkmcnt(1)
	v_fmac_f32_e32 v47, 0x3fb8aa3b, v6
	s_waitcnt lgkmcnt(0)
	v_fmac_f32_e32 v127, 0x3fb8aa3b, v7
	v_max3_f32 v42, v34, v40, v41
	v_add_f32_e32 v34, v131, v47
	v_add_f32_e32 v35, v134, v127
	v_max3_f32 v42, v42, v34, v35
	v_or_b32_e32 v43, 16, v125
	v_sub_u32_e32 v43, v130, v43
	v_cmp_lt_i32_e32 vcc, s67, v43
	v_or_b32_e32 v45, 17, v125
	s_and_b64 vcc, s[0:1], vcc
	v_sub_u32_e32 v45, v130, v45
	v_med3_i32 v44, v43, -1, v209
	v_cndmask_b32_e32 v43, 0, v211, vcc
	v_cmp_lt_i32_e32 vcc, s67, v45
	v_or_b32_e32 v47, 18, v125
	s_and_b64 vcc, s[0:1], vcc
	v_sub_u32_e32 v47, v130, v47
	v_med3_i32 v46, v45, -1, v209
	v_cndmask_b32_e32 v45, 0, v211, vcc
	v_cmp_lt_i32_e32 vcc, s67, v47
	v_or_b32_e32 v129, 19, v125
	s_and_b64 vcc, s[0:1], vcc
	v_sub_u32_e32 v129, v130, v129
	v_med3_i32 v127, v47, -1, v209
	v_cndmask_b32_e32 v47, 0, v211, vcc
	v_cmp_lt_i32_e32 vcc, s67, v129
	v_or_b32_e32 v134, 24, v125
	s_and_b64 vcc, s[0:1], vcc
	v_sub_u32_e32 v134, v130, v134
	v_med3_i32 v131, v129, -1, v209
	v_cndmask_b32_e32 v129, 0, v211, vcc
	v_med3_i32 v135, v134, -1, v209
	v_cmp_lt_i32_e32 vcc, s67, v134
	v_or_b32_e32 v134, 25, v125
	s_and_b64 vcc, s[0:1], vcc
	v_sub_u32_e32 v134, v130, v134
	v_cndmask_b32_e32 v136, 0, v211, vcc
	v_med3_i32 v137, v134, -1, v209
	v_cmp_lt_i32_e32 vcc, s67, v134
	v_or_b32_e32 v134, 26, v125
	s_and_b64 vcc, s[0:1], vcc
	v_sub_u32_e32 v134, v130, v134
	v_cndmask_b32_e32 v138, 0, v211, vcc
	v_med3_i32 v139, v134, -1, v209
	v_cmp_lt_i32_e32 vcc, s67, v134
	v_or_b32_e32 v134, 27, v125
	v_sub_u32_e32 v134, v130, v134
	v_med3_i32 v140, v134, -1, v209
	v_lshl_add_u32 v44, v44, 2, s69
	v_lshl_add_u32 v46, v46, 2, s69
	v_lshl_add_u32 v127, v127, 2, s69
	v_lshl_add_u32 v131, v131, 2, s69
	v_lshl_add_u32 v137, v137, 2, s69
	v_lshl_add_u32 v139, v139, 2, s69
	v_lshl_add_u32 v140, v140, 2, s69
	v_lshl_add_u32 v135, v135, 2, s69
	ds_read_b32 v44, v44 offset:256
	ds_read_b32 v46, v46 offset:256
	ds_read_b32 v127, v127 offset:256
	ds_read_b32 v131, v131 offset:256
	ds_read_b32 v141, v135 offset:256
	ds_read_b32 v137, v137 offset:256
	ds_read_b32 v139, v139 offset:256
	ds_read_b32 v140, v140 offset:256
	s_and_b64 vcc, s[0:1], vcc
	v_cndmask_b32_e32 v142, 0, v211, vcc
	v_cmp_lt_i32_e32 vcc, s67, v134
	s_and_b64 vcc, s[0:1], vcc
	s_nop 0
	v_cndmask_b32_e32 v143, 0, v211, vcc
	s_waitcnt lgkmcnt(7)
	v_fmac_f32_e32 v44, 0x3fb8aa3b, v8
	s_waitcnt lgkmcnt(6)
	v_fmac_f32_e32 v46, 0x3fb8aa3b, v9
	v_add_f32_e32 v134, v43, v44
	v_add_f32_e32 v135, v45, v46
	s_waitcnt lgkmcnt(5)
	v_fmac_f32_e32 v127, 0x3fb8aa3b, v10
	s_waitcnt lgkmcnt(4)
	v_fmac_f32_e32 v131, 0x3fb8aa3b, v11
	v_max3_f32 v42, v42, v134, v135
	v_add_f32_e32 v44, v47, v127
	v_add_f32_e32 v45, v129, v131
	s_waitcnt lgkmcnt(3)
	v_fmac_f32_e32 v141, 0x3fb8aa3b, v12
	s_waitcnt lgkmcnt(2)
	v_fmac_f32_e32 v137, 0x3fb8aa3b, v13
	v_max3_f32 v42, v42, v44, v45
	v_add_f32_e32 v46, v136, v141
	v_add_f32_e32 v47, v138, v137
	s_waitcnt lgkmcnt(1)
	v_fmac_f32_e32 v139, 0x3fb8aa3b, v14
	s_waitcnt lgkmcnt(0)
	v_fmac_f32_e32 v140, 0x3fb8aa3b, v15
	v_max3_f32 v127, v42, v46, v47
	v_add_f32_e32 v42, v142, v139
	v_add_f32_e32 v43, v143, v140
	v_max3_f32 v127, v127, v42, v43
	v_or_b32_e32 v129, 32, v125
	v_sub_u32_e32 v129, v130, v129
	v_cmp_lt_i32_e32 vcc, s67, v129
	v_or_b32_e32 v136, 33, v125
	s_and_b64 vcc, s[0:1], vcc
	v_sub_u32_e32 v136, v130, v136
	v_med3_i32 v131, v129, -1, v209
	v_cndmask_b32_e32 v129, 0, v211, vcc
	v_cmp_lt_i32_e32 vcc, s67, v136
	v_or_b32_e32 v138, 34, v125
	s_and_b64 vcc, s[0:1], vcc
	v_sub_u32_e32 v138, v130, v138
	v_med3_i32 v137, v136, -1, v209
	v_cndmask_b32_e32 v136, 0, v211, vcc
	v_cmp_lt_i32_e32 vcc, s67, v138
	v_or_b32_e32 v140, 35, v125
	s_and_b64 vcc, s[0:1], vcc
	v_sub_u32_e32 v140, v130, v140
	v_med3_i32 v139, v138, -1, v209
	v_cndmask_b32_e32 v138, 0, v211, vcc
	v_cmp_lt_i32_e32 vcc, s67, v140
	v_or_b32_e32 v142, 40, v125
	s_and_b64 vcc, s[0:1], vcc
	v_sub_u32_e32 v142, v130, v142
	v_med3_i32 v141, v140, -1, v209
	v_cndmask_b32_e32 v140, 0, v211, vcc
	v_med3_i32 v143, v142, -1, v209
	v_cmp_lt_i32_e32 vcc, s67, v142
	v_or_b32_e32 v142, 41, v125
	s_and_b64 vcc, s[0:1], vcc
	v_sub_u32_e32 v142, v130, v142
	v_cndmask_b32_e32 v144, 0, v211, vcc
	v_med3_i32 v145, v142, -1, v209
	v_cmp_lt_i32_e32 vcc, s67, v142
	v_or_b32_e32 v142, 42, v125
	s_and_b64 vcc, s[0:1], vcc
	v_sub_u32_e32 v142, v130, v142
	v_cndmask_b32_e32 v146, 0, v211, vcc
	v_med3_i32 v147, v142, -1, v209
	v_cmp_lt_i32_e32 vcc, s67, v142
	v_or_b32_e32 v142, 43, v125
	v_sub_u32_e32 v142, v130, v142
	v_med3_i32 v148, v142, -1, v209
	v_lshl_add_u32 v131, v131, 2, s69
	v_lshl_add_u32 v137, v137, 2, s69
	v_lshl_add_u32 v139, v139, 2, s69
	v_lshl_add_u32 v141, v141, 2, s69
	v_lshl_add_u32 v145, v145, 2, s69
	v_lshl_add_u32 v147, v147, 2, s69
	v_lshl_add_u32 v148, v148, 2, s69
	v_lshl_add_u32 v143, v143, 2, s69
	ds_read_b32 v131, v131 offset:256
	ds_read_b32 v137, v137 offset:256
	ds_read_b32 v139, v139 offset:256
	ds_read_b32 v141, v141 offset:256
	ds_read_b32 v149, v143 offset:256
	ds_read_b32 v145, v145 offset:256
	ds_read_b32 v147, v147 offset:256
	ds_read_b32 v148, v148 offset:256
	s_and_b64 vcc, s[0:1], vcc
	v_cndmask_b32_e32 v150, 0, v211, vcc
	v_cmp_lt_i32_e32 vcc, s67, v142
	s_and_b64 vcc, s[0:1], vcc
	s_nop 0
	v_cndmask_b32_e32 v151, 0, v211, vcc
	s_waitcnt lgkmcnt(7)
	v_fmac_f32_e32 v131, 0x3fb8aa3b, v16
	s_waitcnt lgkmcnt(6)
	v_fmac_f32_e32 v137, 0x3fb8aa3b, v17
	v_add_f32_e32 v142, v129, v131
	v_add_f32_e32 v143, v136, v137
	s_waitcnt lgkmcnt(5)
	v_fmac_f32_e32 v139, 0x3fb8aa3b, v18
	s_waitcnt lgkmcnt(4)
	v_fmac_f32_e32 v141, 0x3fb8aa3b, v19
	v_max3_f32 v127, v127, v142, v143
	v_add_f32_e32 v138, v138, v139
	v_add_f32_e32 v139, v140, v141
	s_waitcnt lgkmcnt(3)
	v_fmac_f32_e32 v149, 0x3fb8aa3b, v20
	s_waitcnt lgkmcnt(2)
	v_fmac_f32_e32 v145, 0x3fb8aa3b, v21
	v_max3_f32 v127, v127, v138, v139
	v_add_f32_e32 v140, v144, v149
	v_add_f32_e32 v141, v146, v145
	s_waitcnt lgkmcnt(1)
	v_fmac_f32_e32 v147, 0x3fb8aa3b, v22
	s_waitcnt lgkmcnt(0)
	v_fmac_f32_e32 v148, 0x3fb8aa3b, v23
	v_max3_f32 v127, v127, v140, v141
	v_add_f32_e32 v136, v150, v147
	v_add_f32_e32 v137, v151, v148
	v_max3_f32 v127, v127, v136, v137
	v_or_b32_e32 v129, 48, v125
	v_sub_u32_e32 v129, v130, v129
	v_cmp_lt_i32_e32 vcc, s67, v129
	v_or_b32_e32 v144, 49, v125
	s_and_b64 vcc, s[0:1], vcc
	v_sub_u32_e32 v144, v130, v144
	v_med3_i32 v131, v129, -1, v209
	v_cndmask_b32_e32 v129, 0, v211, vcc
	v_cmp_lt_i32_e32 vcc, s67, v144
	v_or_b32_e32 v146, 50, v125
	s_and_b64 vcc, s[0:1], vcc
	v_sub_u32_e32 v146, v130, v146
	v_med3_i32 v145, v144, -1, v209
	v_cndmask_b32_e32 v144, 0, v211, vcc
	v_cmp_lt_i32_e32 vcc, s67, v146
	v_or_b32_e32 v148, 51, v125
	s_and_b64 vcc, s[0:1], vcc
	v_sub_u32_e32 v148, v130, v148
	v_med3_i32 v147, v146, -1, v209
	v_cndmask_b32_e32 v146, 0, v211, vcc
	v_cmp_lt_i32_e32 vcc, s67, v148
	v_or_b32_e32 v150, 56, v125
	s_and_b64 vcc, s[0:1], vcc
	v_sub_u32_e32 v150, v130, v150
	v_med3_i32 v149, v148, -1, v209
	v_cndmask_b32_e32 v148, 0, v211, vcc
	v_med3_i32 v151, v150, -1, v209
	v_cmp_lt_i32_e32 vcc, s67, v150
	v_or_b32_e32 v150, 57, v125
	s_and_b64 vcc, s[0:1], vcc
	v_sub_u32_e32 v150, v130, v150
	v_cndmask_b32_e32 v213, 0, v211, vcc
	v_med3_i32 v214, v150, -1, v209
	v_cmp_lt_i32_e32 vcc, s67, v150
	v_or_b32_e32 v150, 58, v125
	v_sub_u32_e32 v150, v130, v150
	v_or_b32_e32 v125, 59, v125
	s_and_b64 vcc, s[0:1], vcc
	v_med3_i32 v216, v150, -1, v209
	v_sub_u32_e32 v125, v130, v125
	v_lshl_add_u32 v131, v131, 2, s69
	v_lshl_add_u32 v145, v145, 2, s69
	v_lshl_add_u32 v147, v147, 2, s69
	v_lshl_add_u32 v149, v149, 2, s69
	v_lshl_add_u32 v214, v214, 2, s69
	v_cndmask_b32_e32 v215, 0, v211, vcc
	v_lshl_add_u32 v216, v216, 2, s69
	v_cmp_lt_i32_e32 vcc, s67, v150
	v_med3_i32 v150, v125, -1, v209
	v_lshl_add_u32 v151, v151, 2, s69
	v_lshl_add_u32 v150, v150, 2, s69
	ds_read_b32 v131, v131 offset:256
	ds_read_b32 v145, v145 offset:256
	ds_read_b32 v147, v147 offset:256
	ds_read_b32 v149, v149 offset:256
	ds_read_b32 v217, v151 offset:256
	ds_read_b32 v214, v214 offset:256
	ds_read_b32 v216, v216 offset:256
	ds_read_b32 v218, v150 offset:256
	s_and_b64 vcc, s[0:1], vcc
	v_cndmask_b32_e32 v219, 0, v211, vcc
	v_cmp_lt_i32_e32 vcc, s67, v125
	s_and_b64 vcc, s[0:1], vcc
	s_nop 0
	v_cndmask_b32_e32 v125, 0, v211, vcc
	s_waitcnt lgkmcnt(7)
	v_fmac_f32_e32 v131, 0x3fb8aa3b, v24
	s_waitcnt lgkmcnt(6)
	v_fmac_f32_e32 v145, 0x3fb8aa3b, v25
	v_add_f32_e32 v150, v129, v131
	v_add_f32_e32 v151, v144, v145
	s_waitcnt lgkmcnt(5)
	v_fmac_f32_e32 v147, 0x3fb8aa3b, v26
	s_waitcnt lgkmcnt(4)
	v_fmac_f32_e32 v149, 0x3fb8aa3b, v27
	v_max3_f32 v127, v127, v150, v151
	v_add_f32_e32 v146, v146, v147
	v_add_f32_e32 v147, v148, v149
	s_waitcnt lgkmcnt(3)
	v_fmac_f32_e32 v217, 0x3fb8aa3b, v28
	s_waitcnt lgkmcnt(2)
	v_fmac_f32_e32 v214, 0x3fb8aa3b, v29
	v_max3_f32 v127, v127, v146, v147
	v_add_f32_e32 v148, v213, v217
	v_add_f32_e32 v149, v215, v214
	s_waitcnt lgkmcnt(1)
	v_fmac_f32_e32 v216, 0x3fb8aa3b, v30
	s_waitcnt lgkmcnt(0)
	v_fmac_f32_e32 v218, 0x3fb8aa3b, v31
	v_max3_f32 v127, v127, v148, v149
	v_add_f32_e32 v144, v219, v216
	v_add_f32_e32 v145, v125, v218
	v_max3_f32 v129, v127, v144, v145
	s_mov_b64 s[2:3], 0
.LBB0_1460:
	s_andn2_b64 vcc, exec, s[2:3]
	s_cbranch_vccnz .LBB0_1462
	v_lshl_add_u32 v33, v33, 2, s69
	v_add_u32_e32 v34, 0x80, v33
	ds_read2_b32 v[34:35], v34 offset0:31 offset1:32
	ds_read2_b32 v[36:37], v33 offset0:61 offset1:62
	ds_read2_b32 v[42:43], v33 offset0:53 offset1:54
	ds_read2_b32 v[40:41], v33 offset0:55 offset1:56
	s_waitcnt lgkmcnt(3)
	v_mov_b32_e32 v38, v35
	v_mov_b32_e32 v39, v34
	v_pk_fma_f32 v[38:39], v[0:1], s[44:45], v[38:39] op_sel_hi:[1,0,1]
	s_waitcnt lgkmcnt(2)
	v_mov_b32_e32 v34, v37
	v_mov_b32_e32 v35, v36
	v_max3_f32 v44, v38, s70, v39
	v_pk_fma_f32 v[36:37], v[2:3], s[44:45], v[34:35] op_sel_hi:[1,0,1]
	s_waitcnt lgkmcnt(0)
	v_mov_b32_e32 v34, v41
	v_mov_b32_e32 v35, v40
	v_max3_f32 v44, v44, v36, v37
	v_pk_fma_f32 v[40:41], v[4:5], s[44:45], v[34:35] op_sel_hi:[1,0,1]
	v_mov_b32_e32 v34, v43
	v_mov_b32_e32 v35, v42
	v_max3_f32 v44, v44, v40, v41
	v_pk_fma_f32 v[34:35], v[6:7], s[44:45], v[34:35] op_sel_hi:[1,0,1]
	s_nop 0
	v_max3_f32 v125, v44, v34, v35
	ds_read2_b32 v[42:43], v33 offset0:47 offset1:48
	ds_read2_b32 v[44:45], v33 offset0:45 offset1:46
	ds_read2_b32 v[136:137], v33 offset0:37 offset1:38
	ds_read2_b32 v[46:47], v33 offset0:39 offset1:40
	s_waitcnt lgkmcnt(3)
	v_mov_b32_e32 v134, v43
	v_mov_b32_e32 v135, v42
	v_pk_fma_f32 v[134:135], v[8:9], s[44:45], v[134:135] op_sel_hi:[1,0,1]
	s_waitcnt lgkmcnt(2)
	v_mov_b32_e32 v42, v45
	v_mov_b32_e32 v43, v44
	v_max3_f32 v125, v125, v134, v135
	v_pk_fma_f32 v[44:45], v[10:11], s[44:45], v[42:43] op_sel_hi:[1,0,1]
	s_waitcnt lgkmcnt(0)
	v_mov_b32_e32 v42, v47
	v_mov_b32_e32 v43, v46
	v_max3_f32 v125, v125, v44, v45
	v_pk_fma_f32 v[46:47], v[12:13], s[44:45], v[42:43] op_sel_hi:[1,0,1]
	v_mov_b32_e32 v42, v137
	v_mov_b32_e32 v43, v136
	v_max3_f32 v125, v125, v46, v47
	v_pk_fma_f32 v[42:43], v[14:15], s[44:45], v[42:43] op_sel_hi:[1,0,1]
	s_nop 0
	v_max3_f32 v125, v125, v42, v43
	ds_read2_b32 v[136:137], v33 offset0:31 offset1:32
	ds_read2_b32 v[138:139], v33 offset0:29 offset1:30
	ds_read2_b32 v[144:145], v33 offset0:21 offset1:22
	ds_read2_b32 v[140:141], v33 offset0:23 offset1:24
	s_waitcnt lgkmcnt(3)
	v_mov_b32_e32 v142, v137
	v_mov_b32_e32 v143, v136
	v_pk_fma_f32 v[142:143], v[16:17], s[44:45], v[142:143] op_sel_hi:[1,0,1]
	s_waitcnt lgkmcnt(2)
	v_mov_b32_e32 v136, v139
	v_mov_b32_e32 v137, v138
	v_max3_f32 v125, v125, v142, v143
	v_pk_fma_f32 v[138:139], v[18:19], s[44:45], v[136:137] op_sel_hi:[1,0,1]
	s_waitcnt lgkmcnt(0)
	v_mov_b32_e32 v136, v141
	v_mov_b32_e32 v137, v140
	v_max3_f32 v125, v125, v138, v139
	v_pk_fma_f32 v[140:141], v[20:21], s[44:45], v[136:137] op_sel_hi:[1,0,1]
	v_mov_b32_e32 v136, v145
	v_mov_b32_e32 v137, v144
	v_max3_f32 v125, v125, v140, v141
	v_pk_fma_f32 v[136:137], v[22:23], s[44:45], v[136:137] op_sel_hi:[1,0,1]
	s_nop 0
	v_max3_f32 v125, v125, v136, v137
	ds_read2_b32 v[144:145], v33 offset0:15 offset1:16
	ds_read2_b32 v[146:147], v33 offset0:13 offset1:14
	ds_read2_b32 v[214:215], v33 offset0:5 offset1:6
	ds_read2_b32 v[148:149], v33 offset0:7 offset1:8
	s_waitcnt lgkmcnt(3)
	v_mov_b32_e32 v150, v145
	v_mov_b32_e32 v151, v144
	v_pk_fma_f32 v[150:151], v[24:25], s[44:45], v[150:151] op_sel_hi:[1,0,1]
	s_waitcnt lgkmcnt(2)
	v_mov_b32_e32 v144, v147
	v_mov_b32_e32 v145, v146
	v_max3_f32 v33, v125, v150, v151
	v_pk_fma_f32 v[146:147], v[26:27], s[44:45], v[144:145] op_sel_hi:[1,0,1]
	s_waitcnt lgkmcnt(0)
	v_mov_b32_e32 v144, v149
	v_mov_b32_e32 v145, v148
	v_max3_f32 v33, v33, v146, v147
	v_pk_fma_f32 v[148:149], v[28:29], s[44:45], v[144:145] op_sel_hi:[1,0,1]
	v_mov_b32_e32 v144, v215
	v_mov_b32_e32 v145, v214
	v_max3_f32 v33, v33, v148, v149
	v_pk_fma_f32 v[144:145], v[30:31], s[44:45], v[144:145] op_sel_hi:[1,0,1]
	s_nop 0
	v_max3_f32 v129, v33, v144, v145

.LBB0_1463:
	v_mov_b32_e32 v127, 0
.LBB0_1465:
	v_lshrrev_b32_e32 v0, s40, v104
	v_and_b32_e32 v0, 1, v0
	v_cmp_eq_u32_e32 vcc, 1, v0
	s_or_b64 s[0:1], s[0:1], vcc
	v_cndmask_b32_e64 v0, v211, v129, s[0:1]
	ds_bpermute_b32 v1, v155, v0
	s_mov_b64 s[2:3], -1
	s_waitcnt lgkmcnt(0)
	v_max3_f32 v33, v123, v0, v1
	v_cmp_neq_f32_e32 vcc, s70, v33
	s_nop 1
	v_cndmask_b32_e32 v125, 0, v33, vcc
	v_cndmask_b32_e64 v31, v212, v125, s[0:1]
	v_sub_f32_e32 v0, v38, v31
	v_exp_f32_e32 v0, v0
	v_sub_f32_e32 v1, v39, v31
	v_exp_f32_e32 v1, v1
	v_sub_f32_e32 v2, v36, v31
	v_exp_f32_e32 v2, v2
	v_add_f32_e32 v3, 0, v0
	v_add_f32_e32 v3, v1, v3
	v_sub_f32_e32 v4, v40, v31
	v_add_f32_e32 v7, v2, v3
	v_sub_f32_e32 v3, v37, v31
	v_exp_f32_e32 v3, v3
	v_exp_f32_e32 v4, v4
	v_sub_f32_e32 v5, v41, v31
	v_exp_f32_e32 v5, v5
	v_sub_f32_e32 v6, v34, v31
	v_exp_f32_e32 v6, v6
	v_add_f32_e32 v7, v3, v7
	v_add_f32_e32 v7, v4, v7
	v_add_f32_e32 v7, v5, v7
	v_add_f32_e32 v11, v6, v7
	v_sub_f32_e32 v7, v35, v31
	v_exp_f32_e32 v7, v7
	v_sub_f32_e32 v8, v134, v31
	v_exp_f32_e32 v8, v8
	v_sub_f32_e32 v9, v135, v31
	v_exp_f32_e32 v9, v9
	v_sub_f32_e32 v10, v44, v31
	v_exp_f32_e32 v10, v10
	v_add_f32_e32 v11, v7, v11
	v_add_f32_e32 v11, v8, v11
	v_add_f32_e32 v11, v9, v11
	v_add_f32_e32 v15, v10, v11
	v_sub_f32_e32 v11, v45, v31
	v_exp_f32_e32 v11, v11
	v_sub_f32_e32 v12, v46, v31
	v_exp_f32_e32 v12, v12
	v_sub_f32_e32 v13, v47, v31
	v_exp_f32_e32 v13, v13
	v_sub_f32_e32 v14, v42, v31
	v_exp_f32_e32 v14, v14
	v_add_f32_e32 v15, v11, v15
	v_add_f32_e32 v15, v12, v15
	v_add_f32_e32 v15, v13, v15
	v_add_f32_e32 v19, v14, v15
	v_sub_f32_e32 v15, v43, v31
	v_exp_f32_e32 v15, v15
	v_sub_f32_e32 v16, v142, v31
	v_exp_f32_e32 v16, v16
	v_sub_f32_e32 v17, v143, v31
	v_exp_f32_e32 v17, v17
	v_sub_f32_e32 v18, v138, v31
	v_exp_f32_e32 v18, v18
	v_add_f32_e32 v19, v15, v19
	v_add_f32_e32 v19, v16, v19
	v_add_f32_e32 v19, v17, v19
	v_add_f32_e32 v23, v18, v19
	v_sub_f32_e32 v19, v139, v31
	v_exp_f32_e32 v19, v19
	v_sub_f32_e32 v20, v140, v31
	v_exp_f32_e32 v20, v20
	v_sub_f32_e32 v21, v141, v31
	v_exp_f32_e32 v21, v21
	v_sub_f32_e32 v22, v136, v31
	v_exp_f32_e32 v22, v22
	v_add_f32_e32 v23, v19, v23
	v_add_f32_e32 v23, v20, v23
	v_add_f32_e32 v23, v21, v23
	v_add_f32_e32 v27, v22, v23
	v_sub_f32_e32 v23, v137, v31
	v_exp_f32_e32 v23, v23
	v_sub_f32_e32 v24, v150, v31
	v_exp_f32_e32 v24, v24
	v_sub_f32_e32 v25, v151, v31
	v_exp_f32_e32 v25, v25
	v_sub_f32_e32 v26, v146, v31
	v_exp_f32_e32 v26, v26
	v_add_f32_e32 v27, v23, v27
	v_add_f32_e32 v27, v24, v27
	v_add_f32_e32 v27, v25, v27
	v_add_f32_e32 v129, v26, v27
	v_sub_f32_e32 v27, v147, v31
	v_exp_f32_e32 v27, v27
	v_sub_f32_e32 v28, v148, v31
	v_exp_f32_e32 v28, v28
	v_sub_f32_e32 v29, v149, v31
	v_exp_f32_e32 v29, v29
	v_sub_f32_e32 v30, v144, v31
	v_exp_f32_e32 v30, v30
	v_add_f32_e32 v129, v27, v129
	v_add_f32_e32 v129, v28, v129
	v_add_f32_e32 v129, v29, v129
	v_add_f32_e32 v129, v30, v129
	v_sub_f32_e32 v31, v145, v31

.Lfa_fast:
	v_mov_b32_e32 v33, s69
	ds_read_b32 v127, v33 offset:764
	v_max_f32_e32 v252, v0, v1
	v_max3_f32 v252, v252, v2, v3
	v_max3_f32 v252, v252, v4, v5
	v_max3_f32 v252, v252, v6, v7
	v_max3_f32 v252, v252, v8, v9
	v_max3_f32 v252, v252, v10, v11
	v_max3_f32 v252, v252, v12, v13
	v_max3_f32 v252, v252, v14, v15
	v_max3_f32 v252, v252, v16, v17
	v_max3_f32 v252, v252, v18, v19
	v_max3_f32 v252, v252, v20, v21
	v_max3_f32 v252, v252, v22, v23
	v_max3_f32 v252, v252, v24, v25
	v_max3_f32 v252, v252, v26, v27
	v_max3_f32 v252, v252, v28, v29
	v_max3_f32 v252, v252, v30, v31
	v_lshrrev_b32_e32 v253, s40, v104
	v_and_b32_e32 v253, 1, v253
	v_cmp_eq_u32_e32 vcc, 1, v253
	s_or_b64 s[0:1], s[0:1], vcc
	s_waitcnt lgkmcnt(0)
	v_fmamk_f32 v129, v252, 0x3fb8aa3b, v127
	v_cndmask_b32_e64 v252, v211, v129, s[0:1]
	ds_bpermute_b32 v253, v155, v252
	v_add_u32_e32 v47, s37, v204
	ds_read_b64_tr_b16 v[134:135], v47 offset:18432
	ds_read_b64_tr_b16 v[136:137], v47 offset:19584
	ds_read_b64_tr_b16 v[138:139], v47 offset:18496
	ds_read_b64_tr_b16 v[140:141], v47 offset:19648
	ds_read_b64_tr_b16 v[142:143], v47 offset:20736
	ds_read_b64_tr_b16 v[144:145], v47 offset:21888
	ds_read_b64_tr_b16 v[146:147], v47 offset:20800
	ds_read_b64_tr_b16 v[148:149], v47 offset:21952
	s_waitcnt lgkmcnt(8)
	v_max3_f32 v33, v123, v252, v253
	v_cmp_neq_f32_e32 vcc, s70, v33
	s_nop 1
	v_cndmask_b32_e32 v125, 0, v33, vcc
	v_sub_f32_e32 v252, v127, v125
	v_cndmask_b32_e64 v36, v211, v252, s[0:1]
	v_sub_f32_e32 v34, v123, v125
	v_exp_f32_e32 v34, v34
	s_waitcnt lgkmcnt(6)
	ds_read_b64_tr_b16 v[236:237], v47 offset:23040
	ds_read_b64_tr_b16 v[238:239], v47 offset:24192
	ds_read_b64_tr_b16 v[240:241], v47 offset:23104
	ds_read_b64_tr_b16 v[242:243], v47 offset:24256
	ds_read_b64_tr_b16 v[244:245], v47 offset:25344
	ds_read_b64_tr_b16 v[246:247], v47 offset:26496
	ds_read_b64_tr_b16 v[248:249], v47 offset:25408
	ds_read_b64_tr_b16 v[250:251], v47 offset:26560
	v_cmp_neq_f32_e32 vcc, 1.0, v34
	v_mov_b32_e32 v37, 0
	s_cbranch_vccz .Lfa_norescale
	v_pk_mul_f32 v[78:79], v[78:79], v[34:35] op_sel_hi:[1,0]
	v_pk_mul_f32 v[76:77], v[76:77], v[34:35] op_sel_hi:[1,0]
	v_pk_mul_f32 v[74:75], v[74:75], v[34:35] op_sel_hi:[1,0]
	v_pk_mul_f32 v[72:73], v[72:73], v[34:35] op_sel_hi:[1,0]
	v_pk_mul_f32 v[70:71], v[70:71], v[34:35] op_sel_hi:[1,0]
	v_pk_mul_f32 v[68:69], v[68:69], v[34:35] op_sel_hi:[1,0]
	v_pk_mul_f32 v[66:67], v[66:67], v[34:35] op_sel_hi:[1,0]
	v_pk_mul_f32 v[64:65], v[64:65], v[34:35] op_sel_hi:[1,0]
	v_pk_mul_f32 v[62:63], v[62:63], v[34:35] op_sel_hi:[1,0]
	v_pk_mul_f32 v[60:61], v[60:61], v[34:35] op_sel_hi:[1,0]
	v_pk_mul_f32 v[58:59], v[58:59], v[34:35] op_sel_hi:[1,0]
	v_pk_mul_f32 v[56:57], v[56:57], v[34:35] op_sel_hi:[1,0]
	v_pk_mul_f32 v[54:55], v[54:55], v[34:35] op_sel_hi:[1,0]
	v_pk_mul_f32 v[52:53], v[52:53], v[34:35] op_sel_hi:[1,0]
	v_pk_mul_f32 v[50:51], v[50:51], v[34:35] op_sel_hi:[1,0]
	v_pk_mul_f32 v[48:49], v[48:49], v[34:35] op_sel_hi:[1,0]
.Lfa_norescale:
	v_fmamk_f32 v0, v0, 0x3fb8aa3b, v36
	v_fmamk_f32 v1, v1, 0x3fb8aa3b, v36
	v_fmamk_f32 v2, v2, 0x3fb8aa3b, v36
	v_fmamk_f32 v3, v3, 0x3fb8aa3b, v36
	v_fmamk_f32 v4, v4, 0x3fb8aa3b, v36
	v_fmamk_f32 v5, v5, 0x3fb8aa3b, v36
	v_fmamk_f32 v6, v6, 0x3fb8aa3b, v36
	v_fmamk_f32 v7, v7, 0x3fb8aa3b, v36
	v_exp_f32_e32 v0, v0
	v_exp_f32_e32 v1, v1
	v_add_f32_e32 v37, v0, v37
	v_exp_f32_e32 v2, v2
	v_add_f32_e32 v37, v1, v37
	v_exp_f32_e32 v3, v3
	v_add_f32_e32 v37, v2, v37
	v_exp_f32_e32 v4, v4
	v_add_f32_e32 v37, v3, v37
	v_exp_f32_e32 v5, v5
	v_add_f32_e32 v37, v4, v37
	v_exp_f32_e32 v6, v6
	v_add_f32_e32 v37, v5, v37
	v_exp_f32_e32 v7, v7
	v_add_f32_e32 v37, v6, v37
	s_nop 0
	v_add_f32_e32 v37, v7, v37
	v_cvt_pk_bf16_f32 v0, v0, v1
	v_cvt_pk_bf16_f32 v1, v2, v3
	v_cvt_pk_bf16_f32 v2, v4, v5
	v_cvt_pk_bf16_f32 v3, v6, v7
	s_waitcnt lgkmcnt(14)
	s_nop 0
	v_mfma_f32_32x32x16_bf16 v[64:79], v[134:137], v[0:3], v[64:79]
	s_waitcnt lgkmcnt(12)
	v_mfma_f32_32x32x16_bf16 v[48:63], v[138:141], v[0:3], v[48:63]
	v_fmamk_f32 v8, v8, 0x3fb8aa3b, v36
	v_fmamk_f32 v9, v9, 0x3fb8aa3b, v36
	v_fmamk_f32 v10, v10, 0x3fb8aa3b, v36
	v_fmamk_f32 v11, v11, 0x3fb8aa3b, v36
	v_fmamk_f32 v12, v12, 0x3fb8aa3b, v36
	v_fmamk_f32 v13, v13, 0x3fb8aa3b, v36
	v_fmamk_f32 v14, v14, 0x3fb8aa3b, v36
	v_fmamk_f32 v15, v15, 0x3fb8aa3b, v36
	v_exp_f32_e32 v8, v8
	v_exp_f32_e32 v9, v9
	v_add_f32_e32 v37, v8, v37
	v_exp_f32_e32 v10, v10
	v_add_f32_e32 v37, v9, v37
	v_exp_f32_e32 v11, v11
	v_add_f32_e32 v37, v10, v37
	v_exp_f32_e32 v12, v12
	v_add_f32_e32 v37, v11, v37
	v_exp_f32_e32 v13, v13
	v_add_f32_e32 v37, v12, v37
	v_exp_f32_e32 v14, v14
	v_add_f32_e32 v37, v13, v37
	v_exp_f32_e32 v15, v15
	v_add_f32_e32 v37, v14, v37
	s_nop 0
	v_add_f32_e32 v37, v15, v37
	v_cvt_pk_bf16_f32 v8, v8, v9
	v_cvt_pk_bf16_f32 v9, v10, v11
	v_cvt_pk_bf16_f32 v10, v12, v13
	v_cvt_pk_bf16_f32 v11, v14, v15
	s_waitcnt lgkmcnt(10)
	s_nop 0
	v_mfma_f32_32x32x16_bf16 v[64:79], v[142:145], v[8:11], v[64:79]
	s_waitcnt lgkmcnt(8)
	v_mfma_f32_32x32x16_bf16 v[48:63], v[146:149], v[8:11], v[48:63]
	v_fmamk_f32 v16, v16, 0x3fb8aa3b, v36
	v_fmamk_f32 v17, v17, 0x3fb8aa3b, v36
	v_fmamk_f32 v18, v18, 0x3fb8aa3b, v36
	v_fmamk_f32 v19, v19, 0x3fb8aa3b, v36
	v_fmamk_f32 v20, v20, 0x3fb8aa3b, v36
	v_fmamk_f32 v21, v21, 0x3fb8aa3b, v36
	v_fmamk_f32 v22, v22, 0x3fb8aa3b, v36
	v_fmamk_f32 v23, v23, 0x3fb8aa3b, v36
	v_exp_f32_e32 v16, v16
	v_exp_f32_e32 v17, v17
	v_add_f32_e32 v37, v16, v37
	v_exp_f32_e32 v18, v18
	v_add_f32_e32 v37, v17, v37
	v_exp_f32_e32 v19, v19
	v_add_f32_e32 v37, v18, v37
	v_exp_f32_e32 v20, v20
	v_add_f32_e32 v37, v19, v37
	v_exp_f32_e32 v21, v21
	v_add_f32_e32 v37, v20, v37
	v_exp_f32_e32 v22, v22
	v_add_f32_e32 v37, v21, v37
	v_exp_f32_e32 v23, v23
	v_add_f32_e32 v37, v22, v37
	s_nop 0
	v_add_f32_e32 v37, v23, v37
	v_cvt_pk_bf16_f32 v16, v16, v17
	v_cvt_pk_bf16_f32 v17, v18, v19
	v_cvt_pk_bf16_f32 v18, v20, v21
	v_cvt_pk_bf16_f32 v19, v22, v23
	s_waitcnt lgkmcnt(6)
	s_nop 0
	v_mfma_f32_32x32x16_bf16 v[64:79], v[236:239], v[16:19], v[64:79]
	s_waitcnt lgkmcnt(4)
	v_mfma_f32_32x32x16_bf16 v[48:63], v[240:243], v[16:19], v[48:63]
	v_fmamk_f32 v24, v24, 0x3fb8aa3b, v36
	v_fmamk_f32 v25, v25, 0x3fb8aa3b, v36
	v_fmamk_f32 v26, v26, 0x3fb8aa3b, v36
	v_fmamk_f32 v27, v27, 0x3fb8aa3b, v36
	v_fmamk_f32 v28, v28, 0x3fb8aa3b, v36
	v_fmamk_f32 v29, v29, 0x3fb8aa3b, v36
	v_fmamk_f32 v30, v30, 0x3fb8aa3b, v36
	v_fmamk_f32 v31, v31, 0x3fb8aa3b, v36
	v_exp_f32_e32 v24, v24
	v_exp_f32_e32 v25, v25
	v_add_f32_e32 v37, v24, v37
	v_exp_f32_e32 v26, v26
	v_add_f32_e32 v37, v25, v37
	v_exp_f32_e32 v27, v27
	v_add_f32_e32 v37, v26, v37
	v_exp_f32_e32 v28, v28
	v_add_f32_e32 v37, v27, v37
	v_exp_f32_e32 v29, v29
	v_add_f32_e32 v37, v28, v37
	v_exp_f32_e32 v30, v30
	v_add_f32_e32 v37, v29, v37
	v_exp_f32_e32 v31, v31
	v_add_f32_e32 v37, v30, v37
	s_nop 0
	v_add_f32_e32 v37, v31, v37
	v_cvt_pk_bf16_f32 v24, v24, v25
	v_cvt_pk_bf16_f32 v25, v26, v27
	v_cvt_pk_bf16_f32 v26, v28, v29
	v_cvt_pk_bf16_f32 v27, v30, v31
	s_waitcnt lgkmcnt(2)
	s_nop 0
	v_mfma_f32_32x32x16_bf16 v[64:79], v[244:247], v[24:27], v[64:79]
	s_waitcnt lgkmcnt(0)
	v_mfma_f32_32x32x16_bf16 v[48:63], v[248:251], v[24:27], v[48:63]
	v_fmac_f32_e32 v37, v121, v34
	v_mov_b32_e32 v123, v33
	v_mov_b32_e32 v121, v37
	s_branch .LBB0_1470

	.amdhsa_kernel _Z6mk_fwd4Args
		.amdhsa_group_segment_fixed_size 0
		.amdhsa_private_segment_fixed_size 0
		.amdhsa_kernarg_size 448
		.amdhsa_user_sgpr_count 2
		.amdhsa_user_sgpr_dispatch_ptr 0
		.amdhsa_user_sgpr_queue_ptr 0
		.amdhsa_user_sgpr_kernarg_segment_ptr 1
		.amdhsa_user_sgpr_dispatch_id 0
		.amdhsa_user_sgpr_kernarg_preload_length 0
		.amdhsa_user_sgpr_kernarg_preload_offset 0
		.amdhsa_user_sgpr_private_segment_size 0
		.amdhsa_uses_dynamic_stack 0
		.amdhsa_enable_private_segment 0
		.amdhsa_system_sgpr_workgroup_id_x 1
		.amdhsa_system_sgpr_workgroup_id_y 0
		.amdhsa_system_sgpr_workgroup_id_z 0
		.amdhsa_system_sgpr_workgroup_info 0
		.amdhsa_system_vgpr_workitem_id 2
		.amdhsa_next_free_vgpr 256
		.amdhsa_next_free_sgpr 102
		.amdhsa_accum_offset 256
		.amdhsa_reserve_vcc 1
		.amdhsa_float_round_mode_32 0
		.amdhsa_float_round_mode_16_64 0
		.amdhsa_float_denorm_mode_32 3
		.amdhsa_float_denorm_mode_16_64 3
		.amdhsa_dx10_clamp 1
		.amdhsa_ieee_mode 1
		.amdhsa_fp16_overflow 0
		.amdhsa_tg_split 0
		.amdhsa_exception_fp_ieee_invalid_op 0
		.amdhsa_exception_fp_denorm_src 0
		.amdhsa_exception_fp_ieee_div_zero 0
		.amdhsa_exception_fp_ieee_overflow 0
		.amdhsa_exception_fp_ieee_underflow 0
		.amdhsa_exception_fp_ieee_inexact 0
		.amdhsa_exception_int_div_zero 0
	.end_amdhsa_kernel

amdhsa.kernels:
  - .agpr_count:     0
    .args:
      - .offset:         0
        .size:           192
        .value_kind:     by_value
      - .offset:         192
        .size:           4
        .value_kind:     hidden_block_count_x
      - .offset:         196
        .size:           4
        .value_kind:     hidden_block_count_y
      - .offset:         200
        .size:           4
        .value_kind:     hidden_block_count_z
      - .offset:         204
        .size:           2
        .value_kind:     hidden_group_size_x
      - .offset:         206
        .size:           2
        .value_kind:     hidden_group_size_y
      - .offset:         208
        .size:           2
        .value_kind:     hidden_group_size_z
      - .offset:         210
        .size:           2
        .value_kind:     hidden_remainder_x
      - .offset:         212
        .size:           2
        .value_kind:     hidden_remainder_y
      - .offset:         214
        .size:           2
        .value_kind:     hidden_remainder_z
      - .offset:         232
        .size:           8
        .value_kind:     hidden_global_offset_x
      - .offset:         240
        .size:           8
        .value_kind:     hidden_global_offset_y
      - .offset:         248
        .size:           8
        .value_kind:     hidden_global_offset_z
      - .offset:         256
        .size:           2
        .value_kind:     hidden_grid_dims
      - .offset:         280
        .size:           8
        .value_kind:     hidden_multigrid_sync_arg
      - .offset:         312
        .size:           4
        .value_kind:     hidden_dynamic_lds_size
    .group_segment_fixed_size: 0
    .kernarg_segment_align: 8
    .kernarg_segment_size: 448
    .language:       OpenCL C
    .language_version:
      - 2
      - 0
    .max_flat_workgroup_size: 512
    .name:           _Z6mk_fwd4Args
    .private_segment_fixed_size: 0
    .sgpr_count:     108
    .sgpr_spill_count: 123
    .symbol:         _Z6mk_fwd4Args.kd
    .uniform_work_group_size: 1
    .uses_dynamic_stack: false
    .vgpr_count:     256
    .vgpr_spill_count: 0
    .wavefront_size: 64
